# byte-phase pin: every 32-MFMA block of the five GEMM K-loops starts 8-byte aligned (s_nop 0 pads in the load phases)
# speedup vs baseline: 1.0034x; 1.0011x over previous
.LBB0_132:
	ds_read_b128 v[128:131], v179
	ds_read_b128 v[132:135], v179 offset:1024
	ds_read_b128 v[136:139], v179 offset:2048
	ds_read_b128 v[140:143], v179 offset:3072
	ds_read_b128 v[166:169], v180
	ds_read_b128 v[170:173], v180 offset:1024
	ds_read_b128 v[184:187], v180 offset:2048
	ds_read_b128 v[188:191], v180 offset:3072
	s_add_u32 s16, s74, 0xfff00080
	s_addc_u32 s17, s75, -1
	s_cmp_eq_u32 vcc_hi, 60
	s_cselect_b32 s79, s57, s17
	s_cselect_b32 s78, s95, s16
	s_cselect_b32 s77, s55, vcc_lo
	s_cselect_b32 s76, s96, s97
	v_lshl_add_u64 v[174:175], s[74:75], 0, v[158:159]
	s_add_i32 m0, s81, 0xc000
	ds_read_b128 v[192:195], v181
	ds_read_b128 v[196:199], v181 offset:1024
	ds_read_b128 v[200:203], v181 offset:2048
	ds_read_b128 v[206:209], v181 offset:3072
	ds_read_b128 v[210:213], v181 offset:4096
	ds_read_b128 v[214:217], v181 offset:5120
	ds_read_b128 v[218:221], v181 offset:6144
	ds_read_b128 v[222:225], v181 offset:7168
	global_load_lds_dwordx4 v[174:175], off
	v_lshl_add_u64 v[174:175], s[74:75], 0, v[160:161]
	s_add_i32 m0, s81, 0xe000
	s_nop 0
	global_load_lds_dwordx4 v[174:175], off
	s_waitcnt vmcnt(8)
	s_waitcnt lgkmcnt(0)
	s_nop 0
	s_setprio 1
	s_barrier
	v_mfma_f32_16x16x32_bf16 v[124:127], v[128:131], v[192:195], v[124:127]
	v_mfma_f32_16x16x32_bf16 v[120:123], v[136:139], v[192:195], v[120:123]
	v_mfma_f32_16x16x32_bf16 v[108:111], v[128:131], v[200:203], v[108:111]
	v_mfma_f32_16x16x32_bf16 v[104:107], v[136:139], v[200:203], v[104:107]
	v_mfma_f32_16x16x32_bf16 v[92:95], v[128:131], v[210:213], v[92:95]
	v_mfma_f32_16x16x32_bf16 v[88:91], v[136:139], v[210:213], v[88:91]
	v_mfma_f32_16x16x32_bf16 v[76:79], v[128:131], v[218:221], v[76:79]
	v_mfma_f32_16x16x32_bf16 v[72:75], v[136:139], v[218:221], v[72:75]
	v_mfma_f32_16x16x32_bf16 v[124:127], v[132:135], v[196:199], v[124:127]
	v_mfma_f32_16x16x32_bf16 v[120:123], v[140:143], v[196:199], v[120:123]
	v_mfma_f32_16x16x32_bf16 v[108:111], v[132:135], v[206:209], v[108:111]
	v_mfma_f32_16x16x32_bf16 v[104:107], v[140:143], v[206:209], v[104:107]
	v_mfma_f32_16x16x32_bf16 v[92:95], v[132:135], v[214:217], v[92:95]
	v_mfma_f32_16x16x32_bf16 v[88:91], v[140:143], v[214:217], v[88:91]
	v_mfma_f32_16x16x32_bf16 v[76:79], v[132:135], v[222:225], v[76:79]
	v_mfma_f32_16x16x32_bf16 v[72:75], v[140:143], v[222:225], v[72:75]
	v_mfma_f32_16x16x32_bf16 v[116:119], v[166:169], v[192:195], v[116:119]
	v_mfma_f32_16x16x32_bf16 v[112:115], v[184:187], v[192:195], v[112:115]
	v_mfma_f32_16x16x32_bf16 v[100:103], v[166:169], v[200:203], v[100:103]
	v_mfma_f32_16x16x32_bf16 v[96:99], v[184:187], v[200:203], v[96:99]
	v_mfma_f32_16x16x32_bf16 v[84:87], v[166:169], v[210:213], v[84:87]
	v_mfma_f32_16x16x32_bf16 v[80:83], v[184:187], v[210:213], v[80:83]
	v_mfma_f32_16x16x32_bf16 v[68:71], v[166:169], v[218:221], v[68:71]
	v_mfma_f32_16x16x32_bf16 v[64:67], v[184:187], v[218:221], v[64:67]
	v_mfma_f32_16x16x32_bf16 v[116:119], v[170:173], v[196:199], v[116:119]
	v_mfma_f32_16x16x32_bf16 v[112:115], v[188:191], v[196:199], v[112:115]
	v_mfma_f32_16x16x32_bf16 v[100:103], v[170:173], v[206:209], v[100:103]
	v_mfma_f32_16x16x32_bf16 v[96:99], v[188:191], v[206:209], v[96:99]
	v_mfma_f32_16x16x32_bf16 v[84:87], v[170:173], v[214:217], v[84:87]
	v_mfma_f32_16x16x32_bf16 v[80:83], v[188:191], v[214:217], v[80:83]
	v_mfma_f32_16x16x32_bf16 v[68:71], v[170:173], v[222:225], v[68:71]
	v_mfma_f32_16x16x32_bf16 v[64:67], v[188:191], v[222:225], v[64:67]
	s_barrier
	s_setprio 0
	s_add_i32 s16, s93, s80
	v_lshl_add_u64 v[174:175], s[76:77], 0, v[146:147]
	s_mov_b32 m0, s16
	ds_read_b128 v[192:195], v181 offset:16384
	ds_read_b128 v[196:199], v181 offset:17408
	ds_read_b128 v[200:203], v181 offset:18432
	ds_read_b128 v[206:209], v181 offset:19456
	ds_read_b128 v[210:213], v181 offset:20480
	ds_read_b128 v[214:217], v181 offset:21504
	ds_read_b128 v[218:221], v181 offset:22528
	ds_read_b128 v[222:225], v181 offset:23552
	global_load_lds_dwordx4 v[174:175], off
	s_add_i32 m0, s16, 0x2000
	s_add_u32 s16, s76, 0x100000
	v_lshl_add_u64 v[228:229], s[76:77], 0, v[150:151]
	s_addc_u32 s17, s77, 0
	s_add_i32 s3, s94, s80
	global_load_lds_dwordx4 v[228:229], off
	v_lshl_add_u64 v[230:231], s[16:17], 0, v[146:147]
	s_mov_b32 m0, s3
	v_lshl_add_u64 v[232:233], s[78:79], 0, v[148:149]
	global_load_lds_dwordx4 v[230:231], off
	v_lshl_add_u64 v[230:231], s[16:17], 0, v[150:151]
	s_add_i32 m0, s3, 0x2000
	s_nop 0
	global_load_lds_dwordx4 v[230:231], off
	v_lshl_add_u64 v[230:231], s[78:79], 0, v[144:145]
	s_mov_b32 m0, s81
	s_nop 0
	global_load_lds_dwordx4 v[230:231], off
	s_mov_b32 m0, s82
	s_nop 0
	global_load_lds_dwordx4 v[232:233], off
	s_waitcnt vmcnt(8)
	s_waitcnt lgkmcnt(0)
	s_setprio 1
	s_barrier
	v_mfma_f32_16x16x32_bf16 v[60:63], v[128:131], v[192:195], v[60:63]
	v_mfma_f32_16x16x32_bf16 v[56:59], v[136:139], v[192:195], v[56:59]
	v_mfma_f32_16x16x32_bf16 v[44:47], v[128:131], v[200:203], v[44:47]
	v_mfma_f32_16x16x32_bf16 v[40:43], v[136:139], v[200:203], v[40:43]
	v_mfma_f32_16x16x32_bf16 v[28:31], v[128:131], v[210:213], v[28:31]
	v_mfma_f32_16x16x32_bf16 v[24:27], v[136:139], v[210:213], v[24:27]
	v_mfma_f32_16x16x32_bf16 v[12:15], v[128:131], v[218:221], v[12:15]
	v_mfma_f32_16x16x32_bf16 v[8:11], v[136:139], v[218:221], v[8:11]
	v_mfma_f32_16x16x32_bf16 v[60:63], v[132:135], v[196:199], v[60:63]
	v_mfma_f32_16x16x32_bf16 v[56:59], v[140:143], v[196:199], v[56:59]
	v_mfma_f32_16x16x32_bf16 v[44:47], v[132:135], v[206:209], v[44:47]
	v_mfma_f32_16x16x32_bf16 v[40:43], v[140:143], v[206:209], v[40:43]
	v_mfma_f32_16x16x32_bf16 v[28:31], v[132:135], v[214:217], v[28:31]
	v_mfma_f32_16x16x32_bf16 v[24:27], v[140:143], v[214:217], v[24:27]
	v_mfma_f32_16x16x32_bf16 v[12:15], v[132:135], v[222:225], v[12:15]
	v_mfma_f32_16x16x32_bf16 v[8:11], v[140:143], v[222:225], v[8:11]
	v_mfma_f32_16x16x32_bf16 v[52:55], v[166:169], v[192:195], v[52:55]
	v_mfma_f32_16x16x32_bf16 v[48:51], v[184:187], v[192:195], v[48:51]
	v_mfma_f32_16x16x32_bf16 v[36:39], v[166:169], v[200:203], v[36:39]
	v_mfma_f32_16x16x32_bf16 v[32:35], v[184:187], v[200:203], v[32:35]
	v_mfma_f32_16x16x32_bf16 v[20:23], v[166:169], v[210:213], v[20:23]
	v_mfma_f32_16x16x32_bf16 v[16:19], v[184:187], v[210:213], v[16:19]
	v_mfma_f32_16x16x32_bf16 v[4:7], v[166:169], v[218:221], v[4:7]
	v_mfma_f32_16x16x32_bf16 v[0:3], v[184:187], v[218:221], v[0:3]
	v_mfma_f32_16x16x32_bf16 v[52:55], v[170:173], v[196:199], v[52:55]
	v_mfma_f32_16x16x32_bf16 v[48:51], v[188:191], v[196:199], v[48:51]
	v_mfma_f32_16x16x32_bf16 v[36:39], v[170:173], v[206:209], v[36:39]
	v_mfma_f32_16x16x32_bf16 v[32:35], v[188:191], v[206:209], v[32:35]
	v_mfma_f32_16x16x32_bf16 v[20:23], v[170:173], v[214:217], v[20:23]
	v_mfma_f32_16x16x32_bf16 v[16:19], v[188:191], v[214:217], v[16:19]
	v_mfma_f32_16x16x32_bf16 v[4:7], v[170:173], v[222:225], v[4:7]
	v_mfma_f32_16x16x32_bf16 v[0:3], v[188:191], v[222:225], v[0:3]
	s_barrier
	s_setprio 0
	s_add_i32 s3, 0, 0x18000
	s_add_i32 s33, 0, 0x1c000
	v_add_u32_e32 v140, s3, v177
	v_add_u32_e32 v152, s33, v177
	ds_read_b128 v[128:131], v140
	ds_read_b128 v[132:135], v140 offset:1024
	ds_read_b128 v[136:139], v140 offset:2048
	ds_read_b128 v[140:143], v140 offset:3072
	ds_read_b128 v[166:169], v152
	ds_read_b128 v[170:173], v152 offset:1024
	ds_read_b128 v[184:187], v152 offset:2048
	ds_read_b128 v[188:191], v152 offset:3072
	s_add_u32 s16, s78, 0x100000
	s_addc_u32 s17, s79, 0
	s_mov_b32 m0, s83
	v_lshl_add_u64 v[234:235], s[16:17], 0, v[144:145]
	ds_read_b128 v[192:195], v181 offset:32768
	ds_read_b128 v[196:199], v181 offset:33792
	ds_read_b128 v[200:203], v181 offset:34816
	ds_read_b128 v[206:209], v181 offset:35840
	ds_read_b128 v[210:213], v181 offset:36864
	ds_read_b128 v[214:217], v181 offset:37888
	ds_read_b128 v[218:221], v181 offset:38912
	ds_read_b128 v[222:225], v181 offset:39936
	global_load_lds_dwordx4 v[234:235], off
	v_lshl_add_u64 v[234:235], s[16:17], 0, v[148:149]
	s_mov_b32 m0, s84
	s_nop 0
	global_load_lds_dwordx4 v[234:235], off
	s_waitcnt vmcnt(8)
	s_waitcnt lgkmcnt(0)
	s_setprio 1
	s_barrier
	v_mfma_f32_16x16x32_bf16 v[124:127], v[128:131], v[192:195], v[124:127]
	v_mfma_f32_16x16x32_bf16 v[120:123], v[136:139], v[192:195], v[120:123]
	v_mfma_f32_16x16x32_bf16 v[108:111], v[128:131], v[200:203], v[108:111]
	v_mfma_f32_16x16x32_bf16 v[104:107], v[136:139], v[200:203], v[104:107]
	v_mfma_f32_16x16x32_bf16 v[92:95], v[128:131], v[210:213], v[92:95]
	v_mfma_f32_16x16x32_bf16 v[88:91], v[136:139], v[210:213], v[88:91]
	v_mfma_f32_16x16x32_bf16 v[76:79], v[128:131], v[218:221], v[76:79]
	v_mfma_f32_16x16x32_bf16 v[72:75], v[136:139], v[218:221], v[72:75]
	v_mfma_f32_16x16x32_bf16 v[124:127], v[132:135], v[196:199], v[124:127]
	v_mfma_f32_16x16x32_bf16 v[120:123], v[140:143], v[196:199], v[120:123]
	v_mfma_f32_16x16x32_bf16 v[108:111], v[132:135], v[206:209], v[108:111]
	v_mfma_f32_16x16x32_bf16 v[104:107], v[140:143], v[206:209], v[104:107]
	v_mfma_f32_16x16x32_bf16 v[92:95], v[132:135], v[214:217], v[92:95]
	v_mfma_f32_16x16x32_bf16 v[88:91], v[140:143], v[214:217], v[88:91]
	v_mfma_f32_16x16x32_bf16 v[76:79], v[132:135], v[222:225], v[76:79]
	v_mfma_f32_16x16x32_bf16 v[72:75], v[140:143], v[222:225], v[72:75]
	v_mfma_f32_16x16x32_bf16 v[116:119], v[166:169], v[192:195], v[116:119]
	v_mfma_f32_16x16x32_bf16 v[112:115], v[184:187], v[192:195], v[112:115]
	v_mfma_f32_16x16x32_bf16 v[100:103], v[166:169], v[200:203], v[100:103]
	v_mfma_f32_16x16x32_bf16 v[96:99], v[184:187], v[200:203], v[96:99]
	v_mfma_f32_16x16x32_bf16 v[84:87], v[166:169], v[210:213], v[84:87]
	v_mfma_f32_16x16x32_bf16 v[80:83], v[184:187], v[210:213], v[80:83]
	v_mfma_f32_16x16x32_bf16 v[68:71], v[166:169], v[218:221], v[68:71]
	v_mfma_f32_16x16x32_bf16 v[64:67], v[184:187], v[218:221], v[64:67]
	v_mfma_f32_16x16x32_bf16 v[116:119], v[170:173], v[196:199], v[116:119]
	v_mfma_f32_16x16x32_bf16 v[112:115], v[188:191], v[196:199], v[112:115]
	v_mfma_f32_16x16x32_bf16 v[100:103], v[170:173], v[206:209], v[100:103]
	v_mfma_f32_16x16x32_bf16 v[96:99], v[188:191], v[206:209], v[96:99]
	v_mfma_f32_16x16x32_bf16 v[84:87], v[170:173], v[214:217], v[84:87]
	v_mfma_f32_16x16x32_bf16 v[80:83], v[188:191], v[214:217], v[80:83]
	v_mfma_f32_16x16x32_bf16 v[68:71], v[170:173], v[222:225], v[68:71]
	v_mfma_f32_16x16x32_bf16 v[64:67], v[188:191], v[222:225], v[64:67]
	s_barrier
	s_setprio 0
	s_add_i32 s3, s3, s80
	v_lshl_add_u64 v[174:175], v[174:175], 0, s[42:43]
	s_mov_b32 m0, s3
	ds_read_b128 v[192:195], v181 offset:49152
	ds_read_b128 v[196:199], v181 offset:50176
	ds_read_b128 v[200:203], v181 offset:51200
	ds_read_b128 v[206:209], v181 offset:52224
	ds_read_b128 v[210:213], v181 offset:53248
	ds_read_b128 v[214:217], v181 offset:54272
	ds_read_b128 v[218:221], v181 offset:55296
	ds_read_b128 v[222:225], v181 offset:56320
	global_load_lds_dwordx4 v[174:175], off
	s_add_i32 m0, s3, 0x2000
	s_add_u32 s16, s76, 0x100800
	v_lshl_add_u64 v[174:175], v[228:229], 0, s[42:43]
	s_addc_u32 s17, s77, 0
	s_add_i32 s3, s33, s80
	global_load_lds_dwordx4 v[174:175], off
	v_lshl_add_u64 v[174:175], s[16:17], 0, v[146:147]
	s_mov_b32 m0, s3
	s_nop 0
	global_load_lds_dwordx4 v[174:175], off
	v_lshl_add_u64 v[174:175], s[16:17], 0, v[150:151]
	s_add_i32 m0, s3, 0x2000
	s_nop 0
	global_load_lds_dwordx4 v[174:175], off
	v_lshl_add_u64 v[174:175], v[230:231], 0, s[44:45]
	s_mov_b32 m0, s86
	s_nop 0
	global_load_lds_dwordx4 v[174:175], off
	v_lshl_add_u64 v[174:175], v[232:233], 0, s[44:45]
	s_mov_b32 m0, s87
	s_nop 0
	global_load_lds_dwordx4 v[174:175], off
	s_waitcnt vmcnt(8)
	s_waitcnt lgkmcnt(0)
	s_nop 0
	s_setprio 1
	s_barrier
	v_mfma_f32_16x16x32_bf16 v[60:63], v[128:131], v[192:195], v[60:63]
	v_mfma_f32_16x16x32_bf16 v[56:59], v[136:139], v[192:195], v[56:59]
	v_mfma_f32_16x16x32_bf16 v[44:47], v[128:131], v[200:203], v[44:47]
	v_mfma_f32_16x16x32_bf16 v[40:43], v[136:139], v[200:203], v[40:43]
	v_mfma_f32_16x16x32_bf16 v[28:31], v[128:131], v[210:213], v[28:31]
	v_mfma_f32_16x16x32_bf16 v[24:27], v[136:139], v[210:213], v[24:27]
	v_mfma_f32_16x16x32_bf16 v[12:15], v[128:131], v[218:221], v[12:15]
	v_mfma_f32_16x16x32_bf16 v[8:11], v[136:139], v[218:221], v[8:11]
	v_mfma_f32_16x16x32_bf16 v[60:63], v[132:135], v[196:199], v[60:63]
	v_mfma_f32_16x16x32_bf16 v[56:59], v[140:143], v[196:199], v[56:59]
	v_mfma_f32_16x16x32_bf16 v[44:47], v[132:135], v[206:209], v[44:47]
	v_mfma_f32_16x16x32_bf16 v[40:43], v[140:143], v[206:209], v[40:43]
	v_mfma_f32_16x16x32_bf16 v[28:31], v[132:135], v[214:217], v[28:31]
	v_mfma_f32_16x16x32_bf16 v[24:27], v[140:143], v[214:217], v[24:27]
	v_mfma_f32_16x16x32_bf16 v[12:15], v[132:135], v[222:225], v[12:15]
	v_mfma_f32_16x16x32_bf16 v[8:11], v[140:143], v[222:225], v[8:11]
	v_mfma_f32_16x16x32_bf16 v[52:55], v[166:169], v[192:195], v[52:55]
	v_mfma_f32_16x16x32_bf16 v[48:51], v[184:187], v[192:195], v[48:51]
	v_mfma_f32_16x16x32_bf16 v[36:39], v[166:169], v[200:203], v[36:39]
	v_mfma_f32_16x16x32_bf16 v[32:35], v[184:187], v[200:203], v[32:35]
	v_mfma_f32_16x16x32_bf16 v[20:23], v[166:169], v[210:213], v[20:23]
	v_mfma_f32_16x16x32_bf16 v[16:19], v[184:187], v[210:213], v[16:19]
	v_mfma_f32_16x16x32_bf16 v[4:7], v[166:169], v[218:221], v[4:7]
	v_mfma_f32_16x16x32_bf16 v[0:3], v[184:187], v[218:221], v[0:3]
	v_mfma_f32_16x16x32_bf16 v[52:55], v[170:173], v[196:199], v[52:55]
	v_mfma_f32_16x16x32_bf16 v[48:51], v[188:191], v[196:199], v[48:51]
	v_mfma_f32_16x16x32_bf16 v[36:39], v[170:173], v[206:209], v[36:39]
	s_add_i32 vcc_hi, vcc_hi, 2
	v_mfma_f32_16x16x32_bf16 v[32:35], v[188:191], v[206:209], v[32:35]
	s_add_u32 s97, s97, 0x1000
	v_mfma_f32_16x16x32_bf16 v[20:23], v[170:173], v[214:217], v[20:23]
	s_addc_u32 vcc_lo, vcc_lo, 0
	v_mfma_f32_16x16x32_bf16 v[16:19], v[188:191], v[214:217], v[16:19]
	s_add_u32 s74, s74, 0x100
	v_mfma_f32_16x16x32_bf16 v[4:7], v[170:173], v[222:225], v[4:7]
	s_addc_u32 s75, s75, 0
	v_mfma_f32_16x16x32_bf16 v[0:3], v[188:191], v[222:225], v[0:3]
	s_cmp_gt_u32 vcc_hi, 61
	s_barrier
	s_setprio 0
	s_cbranch_scc0 .LBB0_132
	s_and_b64 vcc, exec, s[46:47]
	s_cbranch_vccz .LBB0_135
	s_barrier

.LBB0_432:
	ds_read_b128 v[128:131], v161
	ds_read_b128 v[132:135], v161 offset:1024
	ds_read_b128 v[136:139], v161 offset:2048
	ds_read_b128 v[140:143], v161 offset:3072
	ds_read_b128 v[164:167], v162
	ds_read_b128 v[168:171], v162 offset:1024
	ds_read_b128 v[172:175], v162 offset:2048
	ds_read_b128 v[176:179], v162 offset:3072
	s_add_u32 s3, s70, 0xfff80080
	s_addc_u32 s16, s71, -1
	s_cmp_eq_u32 vcc_hi, 4
	s_cselect_b32 s75, s93, s16
	s_cselect_b32 s74, s94, s3
	s_cselect_b32 s73, s95, vcc_lo
	s_cselect_b32 s72, s96, s97
	v_lshl_add_u64 v[156:157], s[70:71], 0, v[152:153]
	s_add_i32 m0, s1, 0xc000
	ds_read_b128 v[180:183], v163
	ds_read_b128 v[184:187], v163 offset:1024
	ds_read_b128 v[188:191], v163 offset:2048
	ds_read_b128 v[192:195], v163 offset:3072
	ds_read_b128 v[196:199], v163 offset:4096
	ds_read_b128 v[200:203], v163 offset:5120
	ds_read_b128 v[206:209], v163 offset:6144
	ds_read_b128 v[210:213], v163 offset:7168
	global_load_lds_dwordx4 v[156:157], off
	v_lshl_add_u64 v[156:157], s[70:71], 0, v[154:155]
	s_add_i32 m0, s1, 0xe000
	s_nop 0
	global_load_lds_dwordx4 v[156:157], off
	s_waitcnt vmcnt(8)
	s_waitcnt lgkmcnt(0)
	s_setprio 1
	s_barrier
	v_mfma_f32_16x16x32_bf16 v[124:127], v[128:131], v[180:183], v[124:127]
	v_mfma_f32_16x16x32_bf16 v[120:123], v[136:139], v[180:183], v[120:123]
	v_mfma_f32_16x16x32_bf16 v[116:119], v[128:131], v[188:191], v[116:119]
	v_mfma_f32_16x16x32_bf16 v[112:115], v[136:139], v[188:191], v[112:115]
	v_mfma_f32_16x16x32_bf16 v[108:111], v[128:131], v[196:199], v[108:111]
	v_mfma_f32_16x16x32_bf16 v[100:103], v[136:139], v[196:199], v[100:103]
	v_mfma_f32_16x16x32_bf16 v[76:79], v[128:131], v[206:209], v[76:79]
	v_mfma_f32_16x16x32_bf16 v[72:75], v[136:139], v[206:209], v[72:75]
	v_mfma_f32_16x16x32_bf16 v[124:127], v[132:135], v[184:187], v[124:127]
	v_mfma_f32_16x16x32_bf16 v[120:123], v[140:143], v[184:187], v[120:123]
	v_mfma_f32_16x16x32_bf16 v[116:119], v[132:135], v[192:195], v[116:119]
	v_mfma_f32_16x16x32_bf16 v[112:115], v[140:143], v[192:195], v[112:115]
	v_mfma_f32_16x16x32_bf16 v[108:111], v[132:135], v[200:203], v[108:111]
	v_mfma_f32_16x16x32_bf16 v[100:103], v[140:143], v[200:203], v[100:103]
	v_mfma_f32_16x16x32_bf16 v[76:79], v[132:135], v[210:213], v[76:79]
	v_mfma_f32_16x16x32_bf16 v[72:75], v[140:143], v[210:213], v[72:75]
	v_mfma_f32_16x16x32_bf16 v[104:107], v[164:167], v[180:183], v[104:107]
	v_mfma_f32_16x16x32_bf16 v[96:99], v[172:175], v[180:183], v[96:99]
	v_mfma_f32_16x16x32_bf16 v[92:95], v[164:167], v[188:191], v[92:95]
	v_mfma_f32_16x16x32_bf16 v[88:91], v[172:175], v[188:191], v[88:91]
	v_mfma_f32_16x16x32_bf16 v[84:87], v[164:167], v[196:199], v[84:87]
	v_mfma_f32_16x16x32_bf16 v[80:83], v[172:175], v[196:199], v[80:83]
	v_mfma_f32_16x16x32_bf16 v[68:71], v[164:167], v[206:209], v[68:71]
	v_mfma_f32_16x16x32_bf16 v[64:67], v[172:175], v[206:209], v[64:67]
	v_mfma_f32_16x16x32_bf16 v[104:107], v[168:171], v[184:187], v[104:107]
	v_mfma_f32_16x16x32_bf16 v[96:99], v[176:179], v[184:187], v[96:99]
	v_mfma_f32_16x16x32_bf16 v[92:95], v[168:171], v[192:195], v[92:95]
	v_mfma_f32_16x16x32_bf16 v[88:91], v[176:179], v[192:195], v[88:91]
	v_mfma_f32_16x16x32_bf16 v[84:87], v[168:171], v[200:203], v[84:87]
	v_mfma_f32_16x16x32_bf16 v[80:83], v[176:179], v[200:203], v[80:83]
	v_mfma_f32_16x16x32_bf16 v[68:71], v[168:171], v[210:213], v[68:71]
	v_mfma_f32_16x16x32_bf16 v[64:67], v[176:179], v[210:213], v[64:67]
	s_barrier
	s_setprio 0
	s_add_i32 s3, s85, s19
	v_lshl_add_u64 v[156:157], s[72:73], 0, v[148:149]
	s_mov_b32 m0, s3
	ds_read_b128 v[180:183], v163 offset:16384
	ds_read_b128 v[184:187], v163 offset:17408
	ds_read_b128 v[188:191], v163 offset:18432
	ds_read_b128 v[192:195], v163 offset:19456
	ds_read_b128 v[196:199], v163 offset:20480
	ds_read_b128 v[200:203], v163 offset:21504
	ds_read_b128 v[206:209], v163 offset:22528
	ds_read_b128 v[210:213], v163 offset:23552
	global_load_lds_dwordx4 v[156:157], off
	s_add_i32 m0, s3, 0x2000
	s_add_u32 s16, s72, 0x20000
	v_lshl_add_u64 v[214:215], s[72:73], 0, v[144:145]
	s_addc_u32 s17, s73, 0
	s_add_i32 s3, s86, s19
	global_load_lds_dwordx4 v[214:215], off
	v_lshl_add_u64 v[216:217], s[16:17], 0, v[148:149]
	s_mov_b32 m0, s3
	v_lshl_add_u64 v[218:219], s[74:75], 0, v[146:147]
	global_load_lds_dwordx4 v[216:217], off
	v_lshl_add_u64 v[216:217], s[16:17], 0, v[144:145]
	s_add_i32 m0, s3, 0x2000
	s_nop 0
	global_load_lds_dwordx4 v[216:217], off
	v_lshl_add_u64 v[216:217], s[74:75], 0, v[150:151]
	s_mov_b32 m0, s1
	s_nop 0
	global_load_lds_dwordx4 v[216:217], off
	s_mov_b32 m0, s79
	s_nop 0
	global_load_lds_dwordx4 v[218:219], off
	s_waitcnt vmcnt(8)
	s_waitcnt lgkmcnt(0)
	s_setprio 1
	s_barrier
	v_mfma_f32_16x16x32_bf16 v[60:63], v[128:131], v[180:183], v[60:63]
	v_mfma_f32_16x16x32_bf16 v[56:59], v[136:139], v[180:183], v[56:59]
	v_mfma_f32_16x16x32_bf16 v[48:51], v[128:131], v[188:191], v[48:51]
	v_mfma_f32_16x16x32_bf16 v[40:43], v[136:139], v[188:191], v[40:43]
	v_mfma_f32_16x16x32_bf16 v[32:35], v[128:131], v[196:199], v[32:35]
	v_mfma_f32_16x16x32_bf16 v[24:27], v[136:139], v[196:199], v[24:27]
	v_mfma_f32_16x16x32_bf16 v[16:19], v[128:131], v[206:209], v[16:19]
	v_mfma_f32_16x16x32_bf16 v[8:11], v[136:139], v[206:209], v[8:11]
	v_mfma_f32_16x16x32_bf16 v[60:63], v[132:135], v[184:187], v[60:63]
	v_mfma_f32_16x16x32_bf16 v[56:59], v[140:143], v[184:187], v[56:59]
	v_mfma_f32_16x16x32_bf16 v[48:51], v[132:135], v[192:195], v[48:51]
	v_mfma_f32_16x16x32_bf16 v[40:43], v[140:143], v[192:195], v[40:43]
	v_mfma_f32_16x16x32_bf16 v[32:35], v[132:135], v[200:203], v[32:35]
	v_mfma_f32_16x16x32_bf16 v[24:27], v[140:143], v[200:203], v[24:27]
	v_mfma_f32_16x16x32_bf16 v[16:19], v[132:135], v[210:213], v[16:19]
	v_mfma_f32_16x16x32_bf16 v[8:11], v[140:143], v[210:213], v[8:11]
	v_mfma_f32_16x16x32_bf16 v[52:55], v[164:167], v[180:183], v[52:55]
	v_mfma_f32_16x16x32_bf16 v[44:47], v[172:175], v[180:183], v[44:47]
	v_mfma_f32_16x16x32_bf16 v[36:39], v[164:167], v[188:191], v[36:39]
	v_mfma_f32_16x16x32_bf16 v[28:31], v[172:175], v[188:191], v[28:31]
	v_mfma_f32_16x16x32_bf16 v[20:23], v[164:167], v[196:199], v[20:23]
	v_mfma_f32_16x16x32_bf16 v[12:15], v[172:175], v[196:199], v[12:15]
	v_mfma_f32_16x16x32_bf16 v[4:7], v[164:167], v[206:209], v[4:7]
	v_mfma_f32_16x16x32_bf16 v[0:3], v[172:175], v[206:209], v[0:3]
	v_mfma_f32_16x16x32_bf16 v[52:55], v[168:171], v[184:187], v[52:55]
	v_mfma_f32_16x16x32_bf16 v[44:47], v[176:179], v[184:187], v[44:47]
	v_mfma_f32_16x16x32_bf16 v[36:39], v[168:171], v[192:195], v[36:39]
	v_mfma_f32_16x16x32_bf16 v[28:31], v[176:179], v[192:195], v[28:31]
	v_mfma_f32_16x16x32_bf16 v[20:23], v[168:171], v[200:203], v[20:23]
	v_mfma_f32_16x16x32_bf16 v[12:15], v[176:179], v[200:203], v[12:15]
	v_mfma_f32_16x16x32_bf16 v[4:7], v[168:171], v[210:213], v[4:7]
	v_mfma_f32_16x16x32_bf16 v[0:3], v[176:179], v[210:213], v[0:3]
	s_barrier
	s_setprio 0
	s_add_i32 s3, 0, 0x18000
	s_add_i32 s33, 0, 0x1c000
	v_add_u32_e32 v140, s3, v159
	v_add_u32_e32 v176, s33, v159
	ds_read_b128 v[128:131], v140
	ds_read_b128 v[132:135], v140 offset:1024
	ds_read_b128 v[136:139], v140 offset:2048
	ds_read_b128 v[140:143], v140 offset:3072
	ds_read_b128 v[164:167], v176
	ds_read_b128 v[168:171], v176 offset:1024
	ds_read_b128 v[172:175], v176 offset:2048
	ds_read_b128 v[176:179], v176 offset:3072
	s_add_u32 s16, s74, 0x80000
	s_addc_u32 s17, s75, 0
	s_mov_b32 m0, s80
	v_lshl_add_u64 v[220:221], s[16:17], 0, v[150:151]
	ds_read_b128 v[180:183], v163 offset:32768
	ds_read_b128 v[184:187], v163 offset:33792
	ds_read_b128 v[188:191], v163 offset:34816
	ds_read_b128 v[192:195], v163 offset:35840
	ds_read_b128 v[196:199], v163 offset:36864
	ds_read_b128 v[200:203], v163 offset:37888
	ds_read_b128 v[206:209], v163 offset:38912
	ds_read_b128 v[210:213], v163 offset:39936
	global_load_lds_dwordx4 v[220:221], off
	v_lshl_add_u64 v[220:221], s[16:17], 0, v[146:147]
	s_mov_b32 m0, s81
	s_nop 0
	global_load_lds_dwordx4 v[220:221], off
	s_waitcnt vmcnt(8)
	s_waitcnt lgkmcnt(0)
	s_setprio 1
	s_barrier
	v_mfma_f32_16x16x32_bf16 v[124:127], v[128:131], v[180:183], v[124:127]
	v_mfma_f32_16x16x32_bf16 v[120:123], v[136:139], v[180:183], v[120:123]
	v_mfma_f32_16x16x32_bf16 v[116:119], v[128:131], v[188:191], v[116:119]
	v_mfma_f32_16x16x32_bf16 v[112:115], v[136:139], v[188:191], v[112:115]
	v_mfma_f32_16x16x32_bf16 v[108:111], v[128:131], v[196:199], v[108:111]
	v_mfma_f32_16x16x32_bf16 v[100:103], v[136:139], v[196:199], v[100:103]
	v_mfma_f32_16x16x32_bf16 v[76:79], v[128:131], v[206:209], v[76:79]
	v_mfma_f32_16x16x32_bf16 v[72:75], v[136:139], v[206:209], v[72:75]
	v_mfma_f32_16x16x32_bf16 v[124:127], v[132:135], v[184:187], v[124:127]
	v_mfma_f32_16x16x32_bf16 v[120:123], v[140:143], v[184:187], v[120:123]
	v_mfma_f32_16x16x32_bf16 v[116:119], v[132:135], v[192:195], v[116:119]
	v_mfma_f32_16x16x32_bf16 v[112:115], v[140:143], v[192:195], v[112:115]
	v_mfma_f32_16x16x32_bf16 v[108:111], v[132:135], v[200:203], v[108:111]
	v_mfma_f32_16x16x32_bf16 v[100:103], v[140:143], v[200:203], v[100:103]
	v_mfma_f32_16x16x32_bf16 v[76:79], v[132:135], v[210:213], v[76:79]
	v_mfma_f32_16x16x32_bf16 v[72:75], v[140:143], v[210:213], v[72:75]
	v_mfma_f32_16x16x32_bf16 v[104:107], v[164:167], v[180:183], v[104:107]
	v_mfma_f32_16x16x32_bf16 v[96:99], v[172:175], v[180:183], v[96:99]
	v_mfma_f32_16x16x32_bf16 v[92:95], v[164:167], v[188:191], v[92:95]
	v_mfma_f32_16x16x32_bf16 v[88:91], v[172:175], v[188:191], v[88:91]
	v_mfma_f32_16x16x32_bf16 v[84:87], v[164:167], v[196:199], v[84:87]
	v_mfma_f32_16x16x32_bf16 v[80:83], v[172:175], v[196:199], v[80:83]
	v_mfma_f32_16x16x32_bf16 v[68:71], v[164:167], v[206:209], v[68:71]
	v_mfma_f32_16x16x32_bf16 v[64:67], v[172:175], v[206:209], v[64:67]
	v_mfma_f32_16x16x32_bf16 v[104:107], v[168:171], v[184:187], v[104:107]
	v_mfma_f32_16x16x32_bf16 v[96:99], v[176:179], v[184:187], v[96:99]
	v_mfma_f32_16x16x32_bf16 v[92:95], v[168:171], v[192:195], v[92:95]
	v_mfma_f32_16x16x32_bf16 v[88:91], v[176:179], v[192:195], v[88:91]
	v_mfma_f32_16x16x32_bf16 v[84:87], v[168:171], v[200:203], v[84:87]
	v_mfma_f32_16x16x32_bf16 v[80:83], v[176:179], v[200:203], v[80:83]
	v_mfma_f32_16x16x32_bf16 v[68:71], v[168:171], v[210:213], v[68:71]
	v_mfma_f32_16x16x32_bf16 v[64:67], v[176:179], v[210:213], v[64:67]
	s_barrier
	s_setprio 0
	s_add_i32 s3, s3, s19
	v_lshl_add_u64 v[156:157], v[156:157], 0, s[44:45]
	s_mov_b32 m0, s3
	ds_read_b128 v[180:183], v163 offset:49152
	ds_read_b128 v[184:187], v163 offset:50176
	ds_read_b128 v[188:191], v163 offset:51200
	ds_read_b128 v[192:195], v163 offset:52224
	ds_read_b128 v[196:199], v163 offset:53248
	ds_read_b128 v[200:203], v163 offset:54272
	ds_read_b128 v[206:209], v163 offset:55296
	ds_read_b128 v[210:213], v163 offset:56320
	global_load_lds_dwordx4 v[156:157], off
	s_add_i32 m0, s3, 0x2000
	s_add_u32 s16, s72, 0x20800
	v_lshl_add_u64 v[156:157], v[214:215], 0, s[44:45]
	s_addc_u32 s17, s73, 0
	s_add_i32 s3, s33, s19
	global_load_lds_dwordx4 v[156:157], off
	v_lshl_add_u64 v[156:157], s[16:17], 0, v[148:149]
	s_mov_b32 m0, s3
	s_nop 0
	global_load_lds_dwordx4 v[156:157], off
	v_lshl_add_u64 v[156:157], s[16:17], 0, v[144:145]
	s_add_i32 m0, s3, 0x2000
	s_nop 0
	global_load_lds_dwordx4 v[156:157], off
	v_lshl_add_u64 v[156:157], v[216:217], 0, s[46:47]
	s_mov_b32 m0, s83
	s_nop 0
	global_load_lds_dwordx4 v[156:157], off
	v_lshl_add_u64 v[156:157], v[218:219], 0, s[46:47]
	s_mov_b32 m0, s84
	s_nop 0
	global_load_lds_dwordx4 v[156:157], off
	s_waitcnt vmcnt(8)
	s_waitcnt lgkmcnt(0)
	s_nop 0
	s_setprio 1
	s_barrier
	v_mfma_f32_16x16x32_bf16 v[60:63], v[128:131], v[180:183], v[60:63]
	v_mfma_f32_16x16x32_bf16 v[56:59], v[136:139], v[180:183], v[56:59]
	v_mfma_f32_16x16x32_bf16 v[48:51], v[128:131], v[188:191], v[48:51]
	v_mfma_f32_16x16x32_bf16 v[40:43], v[136:139], v[188:191], v[40:43]
	v_mfma_f32_16x16x32_bf16 v[32:35], v[128:131], v[196:199], v[32:35]
	v_mfma_f32_16x16x32_bf16 v[24:27], v[136:139], v[196:199], v[24:27]
	v_mfma_f32_16x16x32_bf16 v[16:19], v[128:131], v[206:209], v[16:19]
	v_mfma_f32_16x16x32_bf16 v[8:11], v[136:139], v[206:209], v[8:11]
	v_mfma_f32_16x16x32_bf16 v[60:63], v[132:135], v[184:187], v[60:63]
	v_mfma_f32_16x16x32_bf16 v[56:59], v[140:143], v[184:187], v[56:59]
	v_mfma_f32_16x16x32_bf16 v[48:51], v[132:135], v[192:195], v[48:51]
	v_mfma_f32_16x16x32_bf16 v[40:43], v[140:143], v[192:195], v[40:43]
	v_mfma_f32_16x16x32_bf16 v[32:35], v[132:135], v[200:203], v[32:35]
	v_mfma_f32_16x16x32_bf16 v[24:27], v[140:143], v[200:203], v[24:27]
	v_mfma_f32_16x16x32_bf16 v[16:19], v[132:135], v[210:213], v[16:19]
	v_mfma_f32_16x16x32_bf16 v[8:11], v[140:143], v[210:213], v[8:11]
	v_mfma_f32_16x16x32_bf16 v[52:55], v[164:167], v[180:183], v[52:55]
	v_mfma_f32_16x16x32_bf16 v[44:47], v[172:175], v[180:183], v[44:47]
	v_mfma_f32_16x16x32_bf16 v[36:39], v[164:167], v[188:191], v[36:39]
	v_mfma_f32_16x16x32_bf16 v[28:31], v[172:175], v[188:191], v[28:31]
	v_mfma_f32_16x16x32_bf16 v[20:23], v[164:167], v[196:199], v[20:23]
	v_mfma_f32_16x16x32_bf16 v[12:15], v[172:175], v[196:199], v[12:15]
	v_mfma_f32_16x16x32_bf16 v[4:7], v[164:167], v[206:209], v[4:7]
	v_mfma_f32_16x16x32_bf16 v[0:3], v[172:175], v[206:209], v[0:3]
	v_mfma_f32_16x16x32_bf16 v[52:55], v[168:171], v[184:187], v[52:55]
	v_mfma_f32_16x16x32_bf16 v[44:47], v[176:179], v[184:187], v[44:47]
	v_mfma_f32_16x16x32_bf16 v[36:39], v[168:171], v[192:195], v[36:39]
	s_add_i32 vcc_hi, vcc_hi, 2
	v_mfma_f32_16x16x32_bf16 v[28:31], v[176:179], v[192:195], v[28:31]
	s_add_u32 s97, s97, 0x1000
	v_mfma_f32_16x16x32_bf16 v[20:23], v[168:171], v[200:203], v[20:23]
	s_addc_u32 vcc_lo, vcc_lo, 0
	v_mfma_f32_16x16x32_bf16 v[12:15], v[176:179], v[200:203], v[12:15]
	s_add_u32 s70, s70, 0x100
	v_mfma_f32_16x16x32_bf16 v[4:7], v[168:171], v[210:213], v[4:7]
	s_addc_u32 s71, s71, 0
	v_mfma_f32_16x16x32_bf16 v[0:3], v[176:179], v[210:213], v[0:3]
	s_cmp_gt_u32 vcc_hi, 5
	s_barrier
	s_setprio 0
	s_cbranch_scc0 .LBB0_432
	s_and_b64 vcc, exec, s[48:49]
	s_cbranch_vccz .LBB0_435
	s_barrier

.LBB0_513:
	ds_read_b128 v[128:131], v230
	ds_read_b128 v[132:135], v230 offset:1024
	ds_read_b128 v[136:139], v230 offset:2048
	ds_read_b128 v[140:143], v230 offset:3072
	ds_read_b128 v[144:147], v231
	ds_read_b128 v[148:151], v231 offset:1024
	ds_read_b128 v[152:155], v231 offset:2048
	ds_read_b128 v[156:159], v231 offset:3072
	s_add_u32 s3, s56, 0xfff00080
	s_addc_u32 s16, s57, -1
	s_cmp_eq_u32 s82, 60
	s_cselect_b32 s61, s43, s16
	s_cselect_b32 s60, s49, s3
	s_cselect_b32 s59, s41, s81
	s_cselect_b32 s58, s55, s80
	v_lshl_add_u64 v[214:215], s[56:57], 0, v[196:197]
	s_add_i32 m0, s62, 0xc000
	ds_read_b128 v[160:163], v232
	ds_read_b128 v[164:167], v232 offset:1024
	ds_read_b128 v[168:171], v232 offset:2048
	ds_read_b128 v[172:175], v232 offset:3072
	ds_read_b128 v[176:179], v232 offset:4096
	ds_read_b128 v[180:183], v232 offset:5120
	ds_read_b128 v[206:209], v232 offset:6144
	ds_read_b128 v[210:213], v232 offset:7168
	global_load_lds_dwordx4 v[214:215], off
	v_lshl_add_u64 v[214:215], s[56:57], 0, v[198:199]
	s_add_i32 m0, s62, 0xe000
	s_nop 0
	global_load_lds_dwordx4 v[214:215], off
	s_waitcnt vmcnt(8)
	s_waitcnt lgkmcnt(0)
	s_nop 0
	s_setprio 1
	s_barrier
	v_mfma_f32_16x16x32_bf16 v[124:127], v[128:131], v[160:163], v[124:127]
	v_mfma_f32_16x16x32_bf16 v[120:123], v[136:139], v[160:163], v[120:123]
	v_mfma_f32_16x16x32_bf16 v[108:111], v[128:131], v[168:171], v[108:111]
	v_mfma_f32_16x16x32_bf16 v[104:107], v[136:139], v[168:171], v[104:107]
	v_mfma_f32_16x16x32_bf16 v[92:95], v[128:131], v[176:179], v[92:95]
	v_mfma_f32_16x16x32_bf16 v[88:91], v[136:139], v[176:179], v[88:91]
	v_mfma_f32_16x16x32_bf16 v[76:79], v[128:131], v[206:209], v[76:79]
	v_mfma_f32_16x16x32_bf16 v[72:75], v[136:139], v[206:209], v[72:75]
	v_mfma_f32_16x16x32_bf16 v[124:127], v[132:135], v[164:167], v[124:127]
	v_mfma_f32_16x16x32_bf16 v[120:123], v[140:143], v[164:167], v[120:123]
	v_mfma_f32_16x16x32_bf16 v[108:111], v[132:135], v[172:175], v[108:111]
	v_mfma_f32_16x16x32_bf16 v[104:107], v[140:143], v[172:175], v[104:107]
	v_mfma_f32_16x16x32_bf16 v[92:95], v[132:135], v[180:183], v[92:95]
	v_mfma_f32_16x16x32_bf16 v[88:91], v[140:143], v[180:183], v[88:91]
	v_mfma_f32_16x16x32_bf16 v[76:79], v[132:135], v[210:213], v[76:79]
	v_mfma_f32_16x16x32_bf16 v[72:75], v[140:143], v[210:213], v[72:75]
	v_mfma_f32_16x16x32_bf16 v[116:119], v[144:147], v[160:163], v[116:119]
	v_mfma_f32_16x16x32_bf16 v[112:115], v[152:155], v[160:163], v[112:115]
	v_mfma_f32_16x16x32_bf16 v[100:103], v[144:147], v[168:171], v[100:103]
	v_mfma_f32_16x16x32_bf16 v[96:99], v[152:155], v[168:171], v[96:99]
	v_mfma_f32_16x16x32_bf16 v[84:87], v[144:147], v[176:179], v[84:87]
	v_mfma_f32_16x16x32_bf16 v[80:83], v[152:155], v[176:179], v[80:83]
	v_mfma_f32_16x16x32_bf16 v[68:71], v[144:147], v[206:209], v[68:71]
	v_mfma_f32_16x16x32_bf16 v[64:67], v[152:155], v[206:209], v[64:67]
	v_mfma_f32_16x16x32_bf16 v[116:119], v[148:151], v[164:167], v[116:119]
	v_mfma_f32_16x16x32_bf16 v[112:115], v[156:159], v[164:167], v[112:115]
	v_mfma_f32_16x16x32_bf16 v[100:103], v[148:151], v[172:175], v[100:103]
	v_mfma_f32_16x16x32_bf16 v[96:99], v[156:159], v[172:175], v[96:99]
	v_mfma_f32_16x16x32_bf16 v[84:87], v[148:151], v[180:183], v[84:87]
	v_mfma_f32_16x16x32_bf16 v[80:83], v[156:159], v[180:183], v[80:83]
	v_mfma_f32_16x16x32_bf16 v[68:71], v[148:151], v[210:213], v[68:71]
	v_mfma_f32_16x16x32_bf16 v[64:67], v[156:159], v[210:213], v[64:67]
	s_barrier
	s_setprio 0
	s_add_i32 s3, s75, s19
	v_lshl_add_u64 v[214:215], s[58:59], 0, v[186:187]
	s_mov_b32 m0, s3
	ds_read_b128 v[160:163], v232 offset:16384
	ds_read_b128 v[164:167], v232 offset:17408
	ds_read_b128 v[168:171], v232 offset:18432
	ds_read_b128 v[172:175], v232 offset:19456
	ds_read_b128 v[176:179], v232 offset:20480
	ds_read_b128 v[180:183], v232 offset:21504
	ds_read_b128 v[206:209], v232 offset:22528
	ds_read_b128 v[210:213], v232 offset:23552
	global_load_lds_dwordx4 v[214:215], off
	s_add_i32 m0, s3, 0x2000
	s_add_u32 s16, s58, 0x100000
	v_lshl_add_u64 v[216:217], s[58:59], 0, v[190:191]
	s_addc_u32 s17, s59, 0
	s_add_i32 s3, s76, s19
	global_load_lds_dwordx4 v[216:217], off
	v_lshl_add_u64 v[218:219], s[16:17], 0, v[186:187]
	s_mov_b32 m0, s3
	v_lshl_add_u64 v[220:221], s[60:61], 0, v[188:189]
	global_load_lds_dwordx4 v[218:219], off
	v_lshl_add_u64 v[218:219], s[16:17], 0, v[190:191]
	s_add_i32 m0, s3, 0x2000
	s_nop 0
	global_load_lds_dwordx4 v[218:219], off
	v_lshl_add_u64 v[218:219], s[60:61], 0, v[184:185]
	s_mov_b32 m0, s62
	s_nop 0
	global_load_lds_dwordx4 v[218:219], off
	s_mov_b32 m0, s63
	s_nop 0
	global_load_lds_dwordx4 v[220:221], off
	s_waitcnt vmcnt(8)
	s_waitcnt lgkmcnt(0)
	s_setprio 1
	s_barrier
	v_mfma_f32_16x16x32_bf16 v[60:63], v[128:131], v[160:163], v[60:63]
	v_mfma_f32_16x16x32_bf16 v[56:59], v[136:139], v[160:163], v[56:59]
	v_mfma_f32_16x16x32_bf16 v[44:47], v[128:131], v[168:171], v[44:47]
	v_mfma_f32_16x16x32_bf16 v[40:43], v[136:139], v[168:171], v[40:43]
	v_mfma_f32_16x16x32_bf16 v[28:31], v[128:131], v[176:179], v[28:31]
	v_mfma_f32_16x16x32_bf16 v[24:27], v[136:139], v[176:179], v[24:27]
	v_mfma_f32_16x16x32_bf16 v[12:15], v[128:131], v[206:209], v[12:15]
	v_mfma_f32_16x16x32_bf16 v[8:11], v[136:139], v[206:209], v[8:11]
	v_mfma_f32_16x16x32_bf16 v[60:63], v[132:135], v[164:167], v[60:63]
	v_mfma_f32_16x16x32_bf16 v[56:59], v[140:143], v[164:167], v[56:59]
	v_mfma_f32_16x16x32_bf16 v[44:47], v[132:135], v[172:175], v[44:47]
	v_mfma_f32_16x16x32_bf16 v[40:43], v[140:143], v[172:175], v[40:43]
	v_mfma_f32_16x16x32_bf16 v[28:31], v[132:135], v[180:183], v[28:31]
	v_mfma_f32_16x16x32_bf16 v[24:27], v[140:143], v[180:183], v[24:27]
	v_mfma_f32_16x16x32_bf16 v[12:15], v[132:135], v[210:213], v[12:15]
	v_mfma_f32_16x16x32_bf16 v[8:11], v[140:143], v[210:213], v[8:11]
	v_mfma_f32_16x16x32_bf16 v[52:55], v[144:147], v[160:163], v[52:55]
	v_mfma_f32_16x16x32_bf16 v[48:51], v[152:155], v[160:163], v[48:51]
	v_mfma_f32_16x16x32_bf16 v[36:39], v[144:147], v[168:171], v[36:39]
	v_mfma_f32_16x16x32_bf16 v[32:35], v[152:155], v[168:171], v[32:35]
	v_mfma_f32_16x16x32_bf16 v[20:23], v[144:147], v[176:179], v[20:23]
	v_mfma_f32_16x16x32_bf16 v[16:19], v[152:155], v[176:179], v[16:19]
	v_mfma_f32_16x16x32_bf16 v[4:7], v[144:147], v[206:209], v[4:7]
	v_mfma_f32_16x16x32_bf16 v[0:3], v[152:155], v[206:209], v[0:3]
	v_mfma_f32_16x16x32_bf16 v[52:55], v[148:151], v[164:167], v[52:55]
	v_mfma_f32_16x16x32_bf16 v[48:51], v[156:159], v[164:167], v[48:51]
	v_mfma_f32_16x16x32_bf16 v[36:39], v[148:151], v[172:175], v[36:39]
	v_mfma_f32_16x16x32_bf16 v[32:35], v[156:159], v[172:175], v[32:35]
	v_mfma_f32_16x16x32_bf16 v[20:23], v[148:151], v[180:183], v[20:23]
	v_mfma_f32_16x16x32_bf16 v[16:19], v[156:159], v[180:183], v[16:19]
	v_mfma_f32_16x16x32_bf16 v[4:7], v[148:151], v[210:213], v[4:7]
	v_mfma_f32_16x16x32_bf16 v[0:3], v[156:159], v[210:213], v[0:3]
	s_barrier
	s_setprio 0
	s_add_i32 s3, 0, 0x18000
	s_add_i32 s33, 0, 0x1c000
	v_add_u32_e32 v140, s3, v229
	v_add_u32_e32 v156, s33, v229
	ds_read_b128 v[128:131], v140
	ds_read_b128 v[132:135], v140 offset:1024
	ds_read_b128 v[136:139], v140 offset:2048
	ds_read_b128 v[140:143], v140 offset:3072
	ds_read_b128 v[144:147], v156
	ds_read_b128 v[148:151], v156 offset:1024
	ds_read_b128 v[152:155], v156 offset:2048
	ds_read_b128 v[156:159], v156 offset:3072
	s_add_u32 s16, s60, 0x100000
	s_addc_u32 s17, s61, 0
	s_mov_b32 m0, s64
	v_lshl_add_u64 v[222:223], s[16:17], 0, v[184:185]
	ds_read_b128 v[160:163], v232 offset:32768
	ds_read_b128 v[164:167], v232 offset:33792
	ds_read_b128 v[168:171], v232 offset:34816
	ds_read_b128 v[172:175], v232 offset:35840
	ds_read_b128 v[176:179], v232 offset:36864
	ds_read_b128 v[180:183], v232 offset:37888
	ds_read_b128 v[206:209], v232 offset:38912
	ds_read_b128 v[210:213], v232 offset:39936
	global_load_lds_dwordx4 v[222:223], off
	v_lshl_add_u64 v[222:223], s[16:17], 0, v[188:189]
	s_mov_b32 m0, s65
	s_nop 0
	global_load_lds_dwordx4 v[222:223], off
	s_waitcnt vmcnt(8)
	s_waitcnt lgkmcnt(0)
	s_setprio 1
	s_barrier
	v_mfma_f32_16x16x32_bf16 v[124:127], v[128:131], v[160:163], v[124:127]
	v_mfma_f32_16x16x32_bf16 v[120:123], v[136:139], v[160:163], v[120:123]
	v_mfma_f32_16x16x32_bf16 v[108:111], v[128:131], v[168:171], v[108:111]
	v_mfma_f32_16x16x32_bf16 v[104:107], v[136:139], v[168:171], v[104:107]
	v_mfma_f32_16x16x32_bf16 v[92:95], v[128:131], v[176:179], v[92:95]
	v_mfma_f32_16x16x32_bf16 v[88:91], v[136:139], v[176:179], v[88:91]
	v_mfma_f32_16x16x32_bf16 v[76:79], v[128:131], v[206:209], v[76:79]
	v_mfma_f32_16x16x32_bf16 v[72:75], v[136:139], v[206:209], v[72:75]
	v_mfma_f32_16x16x32_bf16 v[124:127], v[132:135], v[164:167], v[124:127]
	v_mfma_f32_16x16x32_bf16 v[120:123], v[140:143], v[164:167], v[120:123]
	v_mfma_f32_16x16x32_bf16 v[108:111], v[132:135], v[172:175], v[108:111]
	v_mfma_f32_16x16x32_bf16 v[104:107], v[140:143], v[172:175], v[104:107]
	v_mfma_f32_16x16x32_bf16 v[92:95], v[132:135], v[180:183], v[92:95]
	v_mfma_f32_16x16x32_bf16 v[88:91], v[140:143], v[180:183], v[88:91]
	v_mfma_f32_16x16x32_bf16 v[76:79], v[132:135], v[210:213], v[76:79]
	v_mfma_f32_16x16x32_bf16 v[72:75], v[140:143], v[210:213], v[72:75]
	v_mfma_f32_16x16x32_bf16 v[116:119], v[144:147], v[160:163], v[116:119]
	v_mfma_f32_16x16x32_bf16 v[112:115], v[152:155], v[160:163], v[112:115]
	v_mfma_f32_16x16x32_bf16 v[100:103], v[144:147], v[168:171], v[100:103]
	v_mfma_f32_16x16x32_bf16 v[96:99], v[152:155], v[168:171], v[96:99]
	v_mfma_f32_16x16x32_bf16 v[84:87], v[144:147], v[176:179], v[84:87]
	v_mfma_f32_16x16x32_bf16 v[80:83], v[152:155], v[176:179], v[80:83]
	v_mfma_f32_16x16x32_bf16 v[68:71], v[144:147], v[206:209], v[68:71]
	v_mfma_f32_16x16x32_bf16 v[64:67], v[152:155], v[206:209], v[64:67]
	v_mfma_f32_16x16x32_bf16 v[116:119], v[148:151], v[164:167], v[116:119]
	v_mfma_f32_16x16x32_bf16 v[112:115], v[156:159], v[164:167], v[112:115]
	v_mfma_f32_16x16x32_bf16 v[100:103], v[148:151], v[172:175], v[100:103]
	v_mfma_f32_16x16x32_bf16 v[96:99], v[156:159], v[172:175], v[96:99]
	v_mfma_f32_16x16x32_bf16 v[84:87], v[148:151], v[180:183], v[84:87]
	v_mfma_f32_16x16x32_bf16 v[80:83], v[156:159], v[180:183], v[80:83]
	v_mfma_f32_16x16x32_bf16 v[68:71], v[148:151], v[210:213], v[68:71]
	v_mfma_f32_16x16x32_bf16 v[64:67], v[156:159], v[210:213], v[64:67]
	s_barrier
	s_setprio 0
	s_add_i32 s3, s3, s19
	v_lshl_add_u64 v[214:215], v[214:215], 0, s[14:15]
	s_mov_b32 m0, s3
	ds_read_b128 v[160:163], v232 offset:49152
	ds_read_b128 v[164:167], v232 offset:50176
	ds_read_b128 v[168:171], v232 offset:51200
	ds_read_b128 v[172:175], v232 offset:52224
	ds_read_b128 v[176:179], v232 offset:53248
	ds_read_b128 v[180:183], v232 offset:54272
	ds_read_b128 v[206:209], v232 offset:55296
	ds_read_b128 v[210:213], v232 offset:56320
	global_load_lds_dwordx4 v[214:215], off
	s_add_i32 m0, s3, 0x2000
	s_add_u32 s16, s58, 0x100800
	v_lshl_add_u64 v[214:215], v[216:217], 0, s[14:15]
	s_addc_u32 s17, s59, 0
	s_add_i32 s3, s33, s19
	global_load_lds_dwordx4 v[214:215], off
	v_lshl_add_u64 v[214:215], s[16:17], 0, v[186:187]
	s_mov_b32 m0, s3
	s_nop 0
	global_load_lds_dwordx4 v[214:215], off
	v_lshl_add_u64 v[214:215], s[16:17], 0, v[190:191]
	s_add_i32 m0, s3, 0x2000
	s_nop 0
	global_load_lds_dwordx4 v[214:215], off
	v_lshl_add_u64 v[214:215], v[218:219], 0, s[36:37]
	s_mov_b32 m0, s70
	s_nop 0
	global_load_lds_dwordx4 v[214:215], off
	v_lshl_add_u64 v[214:215], v[220:221], 0, s[36:37]
	s_mov_b32 m0, s71
	s_nop 0
	global_load_lds_dwordx4 v[214:215], off
	s_waitcnt vmcnt(8)
	s_waitcnt lgkmcnt(0)
	s_nop 0
	s_setprio 1
	s_barrier
	v_mfma_f32_16x16x32_bf16 v[60:63], v[128:131], v[160:163], v[60:63]
	v_mfma_f32_16x16x32_bf16 v[56:59], v[136:139], v[160:163], v[56:59]
	v_mfma_f32_16x16x32_bf16 v[44:47], v[128:131], v[168:171], v[44:47]
	v_mfma_f32_16x16x32_bf16 v[40:43], v[136:139], v[168:171], v[40:43]
	v_mfma_f32_16x16x32_bf16 v[28:31], v[128:131], v[176:179], v[28:31]
	v_mfma_f32_16x16x32_bf16 v[24:27], v[136:139], v[176:179], v[24:27]
	v_mfma_f32_16x16x32_bf16 v[12:15], v[128:131], v[206:209], v[12:15]
	v_mfma_f32_16x16x32_bf16 v[8:11], v[136:139], v[206:209], v[8:11]
	v_mfma_f32_16x16x32_bf16 v[60:63], v[132:135], v[164:167], v[60:63]
	v_mfma_f32_16x16x32_bf16 v[56:59], v[140:143], v[164:167], v[56:59]
	v_mfma_f32_16x16x32_bf16 v[44:47], v[132:135], v[172:175], v[44:47]
	v_mfma_f32_16x16x32_bf16 v[40:43], v[140:143], v[172:175], v[40:43]
	v_mfma_f32_16x16x32_bf16 v[28:31], v[132:135], v[180:183], v[28:31]
	v_mfma_f32_16x16x32_bf16 v[24:27], v[140:143], v[180:183], v[24:27]
	v_mfma_f32_16x16x32_bf16 v[12:15], v[132:135], v[210:213], v[12:15]
	v_mfma_f32_16x16x32_bf16 v[8:11], v[140:143], v[210:213], v[8:11]
	v_mfma_f32_16x16x32_bf16 v[52:55], v[144:147], v[160:163], v[52:55]
	v_mfma_f32_16x16x32_bf16 v[48:51], v[152:155], v[160:163], v[48:51]
	v_mfma_f32_16x16x32_bf16 v[36:39], v[144:147], v[168:171], v[36:39]
	v_mfma_f32_16x16x32_bf16 v[32:35], v[152:155], v[168:171], v[32:35]
	v_mfma_f32_16x16x32_bf16 v[20:23], v[144:147], v[176:179], v[20:23]
	v_mfma_f32_16x16x32_bf16 v[16:19], v[152:155], v[176:179], v[16:19]
	v_mfma_f32_16x16x32_bf16 v[4:7], v[144:147], v[206:209], v[4:7]
	v_mfma_f32_16x16x32_bf16 v[0:3], v[152:155], v[206:209], v[0:3]
	v_mfma_f32_16x16x32_bf16 v[52:55], v[148:151], v[164:167], v[52:55]
	v_mfma_f32_16x16x32_bf16 v[48:51], v[156:159], v[164:167], v[48:51]
	v_mfma_f32_16x16x32_bf16 v[36:39], v[148:151], v[172:175], v[36:39]
	s_add_i32 s82, s82, 2
	v_mfma_f32_16x16x32_bf16 v[32:35], v[156:159], v[172:175], v[32:35]
	s_add_u32 s80, s80, 0x1000
	v_mfma_f32_16x16x32_bf16 v[20:23], v[148:151], v[180:183], v[20:23]
	s_addc_u32 s81, s81, 0
	v_mfma_f32_16x16x32_bf16 v[16:19], v[156:159], v[180:183], v[16:19]
	s_add_u32 s56, s56, 0x100
	v_mfma_f32_16x16x32_bf16 v[4:7], v[148:151], v[210:213], v[4:7]
	s_addc_u32 s57, s57, 0
	v_mfma_f32_16x16x32_bf16 v[0:3], v[156:159], v[210:213], v[0:3]
	s_cmp_gt_u32 s82, 61
	s_barrier
	s_setprio 0
	s_cbranch_scc0 .LBB0_513
	s_and_b64 vcc, exec, s[38:39]
	s_cbranch_vccz .LBB0_516
	s_barrier

.Lpf_skip:
	s_add_i32 m0, s66, 0xc000
	ds_read_b128 v[180:183], v190
	ds_read_b128 v[196:199], v190 offset:1024
	ds_read_b128 v[200:203], v190 offset:2048
	ds_read_b128 v[204:207], v190 offset:3072
	ds_read_b128 v[208:211], v190 offset:4096
	ds_read_b128 v[212:215], v190 offset:5120
	ds_read_b128 v[216:219], v190 offset:6144
	ds_read_b128 v[220:223], v190 offset:7168
	global_load_lds_dwordx4 v172, s[14:15]
	s_add_i32 m0, s66, 0xe000
	s_nop 0
	global_load_lds_dwordx4 v174, s[14:15]
	s_waitcnt vmcnt(8)
	s_waitcnt lgkmcnt(0)
	s_nop 0
	s_setprio 1
	s_barrier
	v_mfma_f32_16x16x32_bf16 v[156:159], v[52:55], v[180:183], v[156:159]
	v_mfma_f32_16x16x32_bf16 v[152:155], v[60:63], v[180:183], v[152:155]
	v_mfma_f32_16x16x32_bf16 v[140:143], v[52:55], v[200:203], v[140:143]
	v_mfma_f32_16x16x32_bf16 v[136:139], v[60:63], v[200:203], v[136:139]
	v_mfma_f32_16x16x32_bf16 v[124:127], v[52:55], v[208:211], v[124:127]
	v_mfma_f32_16x16x32_bf16 v[120:123], v[60:63], v[208:211], v[120:123]
	v_mfma_f32_16x16x32_bf16 v[108:111], v[52:55], v[216:219], v[108:111]
	v_mfma_f32_16x16x32_bf16 v[104:107], v[60:63], v[216:219], v[104:107]
	v_mfma_f32_16x16x32_bf16 v[156:159], v[56:59], v[196:199], v[156:159]
	v_mfma_f32_16x16x32_bf16 v[152:155], v[64:67], v[196:199], v[152:155]
	v_mfma_f32_16x16x32_bf16 v[140:143], v[56:59], v[204:207], v[140:143]
	v_mfma_f32_16x16x32_bf16 v[136:139], v[64:67], v[204:207], v[136:139]
	v_mfma_f32_16x16x32_bf16 v[124:127], v[56:59], v[212:215], v[124:127]
	v_mfma_f32_16x16x32_bf16 v[120:123], v[64:67], v[212:215], v[120:123]
	v_mfma_f32_16x16x32_bf16 v[108:111], v[56:59], v[220:223], v[108:111]
	v_mfma_f32_16x16x32_bf16 v[104:107], v[64:67], v[220:223], v[104:107]
	v_mfma_f32_16x16x32_bf16 v[144:147], v[72:75], v[180:183], v[144:147]
	v_mfma_f32_16x16x32_bf16 v[148:151], v[80:83], v[180:183], v[148:151]
	v_mfma_f32_16x16x32_bf16 v[128:131], v[72:75], v[200:203], v[128:131]
	v_mfma_f32_16x16x32_bf16 v[132:135], v[80:83], v[200:203], v[132:135]
	v_mfma_f32_16x16x32_bf16 v[112:115], v[72:75], v[208:211], v[112:115]
	v_mfma_f32_16x16x32_bf16 v[116:119], v[80:83], v[208:211], v[116:119]
	v_mfma_f32_16x16x32_bf16 v[96:99], v[72:75], v[216:219], v[96:99]
	v_mfma_f32_16x16x32_bf16 v[100:103], v[80:83], v[216:219], v[100:103]
	v_mfma_f32_16x16x32_bf16 v[144:147], v[76:79], v[196:199], v[144:147]
	v_mfma_f32_16x16x32_bf16 v[148:151], v[84:87], v[196:199], v[148:151]
	v_mfma_f32_16x16x32_bf16 v[128:131], v[76:79], v[204:207], v[128:131]
	v_mfma_f32_16x16x32_bf16 v[132:135], v[84:87], v[204:207], v[132:135]
	v_mfma_f32_16x16x32_bf16 v[112:115], v[76:79], v[212:215], v[112:115]
	v_mfma_f32_16x16x32_bf16 v[116:119], v[84:87], v[212:215], v[116:119]
	v_mfma_f32_16x16x32_bf16 v[96:99], v[76:79], v[220:223], v[96:99]
	v_mfma_f32_16x16x32_bf16 v[100:103], v[84:87], v[220:223], v[100:103]
	s_barrier
	s_setprio 0
	s_add_i32 s3, s80, s19
	s_mov_b32 m0, s3
	ds_read_b128 v[180:183], v190 offset:16384
	ds_read_b128 v[196:199], v190 offset:17408
	ds_read_b128 v[200:203], v190 offset:18432
	ds_read_b128 v[204:207], v190 offset:19456
	ds_read_b128 v[208:211], v190 offset:20480
	ds_read_b128 v[212:215], v190 offset:21504
	ds_read_b128 v[216:219], v190 offset:22528
	ds_read_b128 v[220:223], v190 offset:23552
	global_load_lds_dwordx4 v162, s[62:63]
	s_add_i32 m0, s3, 0x2000
	s_add_u32 s14, s62, 0x100000
	s_addc_u32 s15, s63, 0
	global_load_lds_dwordx4 v166, s[62:63]
	s_add_i32 s3, s81, s19
	s_mov_b32 m0, s3
	s_nop 0
	global_load_lds_dwordx4 v162, s[14:15]
	s_add_i32 m0, s3, 0x2000
	s_nop 0
	global_load_lds_dwordx4 v166, s[14:15]
	s_mov_b32 m0, s66
	s_nop 0
	global_load_lds_dwordx4 v160, s[64:65]
	s_mov_b32 m0, s67
	s_nop 0
	global_load_lds_dwordx4 v164, s[64:65]
	s_waitcnt vmcnt(8)
	s_waitcnt lgkmcnt(0)
	s_nop 0
	s_setprio 1
	s_barrier
	v_mfma_f32_16x16x32_bf16 v[92:95], v[52:55], v[180:183], v[92:95]
	v_mfma_f32_16x16x32_bf16 v[88:91], v[60:63], v[180:183], v[88:91]
	v_mfma_f32_16x16x32_bf16 v[44:47], v[52:55], v[200:203], v[44:47]
	v_mfma_f32_16x16x32_bf16 v[40:43], v[60:63], v[200:203], v[40:43]
	v_mfma_f32_16x16x32_bf16 v[28:31], v[52:55], v[208:211], v[28:31]
	v_mfma_f32_16x16x32_bf16 v[24:27], v[60:63], v[208:211], v[24:27]
	v_mfma_f32_16x16x32_bf16 v[12:15], v[52:55], v[216:219], v[12:15]
	v_mfma_f32_16x16x32_bf16 v[8:11], v[60:63], v[216:219], v[8:11]
	v_mfma_f32_16x16x32_bf16 v[92:95], v[56:59], v[196:199], v[92:95]
	v_mfma_f32_16x16x32_bf16 v[88:91], v[64:67], v[196:199], v[88:91]
	v_mfma_f32_16x16x32_bf16 v[44:47], v[56:59], v[204:207], v[44:47]
	v_mfma_f32_16x16x32_bf16 v[40:43], v[64:67], v[204:207], v[40:43]
	v_mfma_f32_16x16x32_bf16 v[28:31], v[56:59], v[212:215], v[28:31]
	v_mfma_f32_16x16x32_bf16 v[24:27], v[64:67], v[212:215], v[24:27]
	v_mfma_f32_16x16x32_bf16 v[12:15], v[56:59], v[220:223], v[12:15]
	v_mfma_f32_16x16x32_bf16 v[8:11], v[64:67], v[220:223], v[8:11]
	v_mfma_f32_16x16x32_bf16 v[48:51], v[72:75], v[180:183], v[48:51]
	v_mfma_f32_16x16x32_bf16 v[32:35], v[72:75], v[200:203], v[32:35]
	v_mfma_f32_16x16x32_bf16 v[36:39], v[80:83], v[200:203], v[36:39]
	v_mfma_f32_16x16x32_bf16 v[16:19], v[72:75], v[208:211], v[16:19]
	v_mfma_f32_16x16x32_bf16 v[20:23], v[80:83], v[208:211], v[20:23]
	v_mfma_f32_16x16x32_bf16 v[0:3], v[72:75], v[216:219], v[0:3]
	v_mfma_f32_16x16x32_bf16 v[4:7], v[80:83], v[216:219], v[4:7]
	v_mfma_f32_16x16x32_bf16 v[48:51], v[76:79], v[196:199], v[48:51]
	v_mfma_f32_16x16x32_bf16 v[52:55], v[80:83], v[180:183], v[68:71]
	v_mfma_f32_16x16x32_bf16 v[32:35], v[76:79], v[204:207], v[32:35]
	v_mfma_f32_16x16x32_bf16 v[36:39], v[84:87], v[204:207], v[36:39]
	v_mfma_f32_16x16x32_bf16 v[16:19], v[76:79], v[212:215], v[16:19]
	v_mfma_f32_16x16x32_bf16 v[20:23], v[84:87], v[212:215], v[20:23]
	v_mfma_f32_16x16x32_bf16 v[0:3], v[76:79], v[220:223], v[0:3]
	v_mfma_f32_16x16x32_bf16 v[4:7], v[84:87], v[220:223], v[4:7]
	v_mfma_f32_16x16x32_bf16 v[52:55], v[84:87], v[196:199], v[52:55]
	s_barrier
	s_setprio 0
	s_add_i32 s3, 0, 0x18000
	s_add_i32 s16, 0, 0x1c000
	v_add_u32_e32 v68, s3, v171
	v_add_u32_e32 v84, s16, v171
	s_add_u32 s14, s64, 0x80000
	s_addc_u32 s15, s65, 0
	s_mov_b32 m0, s70
	ds_read_b128 v[56:59], v68
	ds_read_b128 v[60:63], v68 offset:1024
	ds_read_b128 v[64:67], v68 offset:2048
	ds_read_b128 v[68:71], v68 offset:3072
	ds_read_b128 v[72:75], v84
	ds_read_b128 v[76:79], v84 offset:1024
	ds_read_b128 v[80:83], v84 offset:2048
	ds_read_b128 v[84:87], v84 offset:3072
	ds_read_b128 v[180:183], v190 offset:32768
	ds_read_b128 v[196:199], v190 offset:33792
	ds_read_b128 v[200:203], v190 offset:34816
	ds_read_b128 v[204:207], v190 offset:35840
	ds_read_b128 v[208:211], v190 offset:36864
	ds_read_b128 v[212:215], v190 offset:37888
	ds_read_b128 v[216:219], v190 offset:38912
	ds_read_b128 v[220:223], v190 offset:39936
	global_load_lds_dwordx4 v160, s[14:15]
	s_mov_b32 m0, s71
	s_nop 0
	global_load_lds_dwordx4 v164, s[14:15]
	s_waitcnt vmcnt(8)
	s_waitcnt lgkmcnt(0)
	s_setprio 1
	s_barrier
	v_mfma_f32_16x16x32_bf16 v[156:159], v[56:59], v[180:183], v[156:159]
	v_mfma_f32_16x16x32_bf16 v[152:155], v[64:67], v[180:183], v[152:155]
	v_mfma_f32_16x16x32_bf16 v[140:143], v[56:59], v[200:203], v[140:143]
	v_mfma_f32_16x16x32_bf16 v[136:139], v[64:67], v[200:203], v[136:139]
	v_mfma_f32_16x16x32_bf16 v[124:127], v[56:59], v[208:211], v[124:127]
	v_mfma_f32_16x16x32_bf16 v[120:123], v[64:67], v[208:211], v[120:123]
	v_mfma_f32_16x16x32_bf16 v[108:111], v[56:59], v[216:219], v[108:111]
	v_mfma_f32_16x16x32_bf16 v[104:107], v[64:67], v[216:219], v[104:107]
	v_mfma_f32_16x16x32_bf16 v[156:159], v[60:63], v[196:199], v[156:159]
	v_mfma_f32_16x16x32_bf16 v[152:155], v[68:71], v[196:199], v[152:155]
	v_mfma_f32_16x16x32_bf16 v[140:143], v[60:63], v[204:207], v[140:143]
	v_mfma_f32_16x16x32_bf16 v[136:139], v[68:71], v[204:207], v[136:139]
	v_mfma_f32_16x16x32_bf16 v[124:127], v[60:63], v[212:215], v[124:127]
	v_mfma_f32_16x16x32_bf16 v[120:123], v[68:71], v[212:215], v[120:123]
	v_mfma_f32_16x16x32_bf16 v[108:111], v[60:63], v[220:223], v[108:111]
	v_mfma_f32_16x16x32_bf16 v[104:107], v[68:71], v[220:223], v[104:107]
	v_mfma_f32_16x16x32_bf16 v[144:147], v[72:75], v[180:183], v[144:147]
	v_mfma_f32_16x16x32_bf16 v[148:151], v[80:83], v[180:183], v[148:151]
	v_mfma_f32_16x16x32_bf16 v[128:131], v[72:75], v[200:203], v[128:131]
	v_mfma_f32_16x16x32_bf16 v[132:135], v[80:83], v[200:203], v[132:135]
	v_mfma_f32_16x16x32_bf16 v[112:115], v[72:75], v[208:211], v[112:115]
	v_mfma_f32_16x16x32_bf16 v[116:119], v[80:83], v[208:211], v[116:119]
	v_mfma_f32_16x16x32_bf16 v[96:99], v[72:75], v[216:219], v[96:99]
	v_mfma_f32_16x16x32_bf16 v[100:103], v[80:83], v[216:219], v[100:103]
	v_mfma_f32_16x16x32_bf16 v[144:147], v[76:79], v[196:199], v[144:147]
	v_mfma_f32_16x16x32_bf16 v[148:151], v[84:87], v[196:199], v[148:151]
	v_mfma_f32_16x16x32_bf16 v[128:131], v[76:79], v[204:207], v[128:131]
	v_mfma_f32_16x16x32_bf16 v[132:135], v[84:87], v[204:207], v[132:135]
	v_mfma_f32_16x16x32_bf16 v[112:115], v[76:79], v[212:215], v[112:115]
	v_mfma_f32_16x16x32_bf16 v[116:119], v[84:87], v[212:215], v[116:119]
	v_mfma_f32_16x16x32_bf16 v[96:99], v[76:79], v[220:223], v[96:99]
	v_mfma_f32_16x16x32_bf16 v[100:103], v[84:87], v[220:223], v[100:103]
	s_barrier
	s_setprio 0
	s_add_i32 m0, s19, 0x17800
	ds_read_b128 v[180:183], v190 offset:49152
	ds_read_b128 v[196:199], v190 offset:50176
	ds_read_b128 v[200:203], v190 offset:51200
	ds_read_b128 v[204:207], v190 offset:52224
	ds_read_b128 v[208:211], v190 offset:53248
	ds_read_b128 v[212:215], v190 offset:54272
	ds_read_b128 v[216:219], v190 offset:55296
	ds_read_b128 v[220:223], v190 offset:56320
	global_load_lds_dwordx4 v162, s[62:63] offset:2048
	s_add_i32 m0, s19, 0x19800
	s_add_u32 s14, s62, 0x100800
	s_addc_u32 s15, s63, 0
	global_load_lds_dwordx4 v166, s[62:63] offset:2048
	s_add_i32 m0, s19, 0x1c000
	s_nop 0
	global_load_lds_dwordx4 v162, s[14:15]
	s_add_i32 m0, s19, 0x1e000
	s_nop 0
	global_load_lds_dwordx4 v166, s[14:15]
	s_add_i32 m0, s75, 0xfffff800
	s_nop 0
	global_load_lds_dwordx4 v160, s[64:65] offset:2048
	s_add_i32 m0, s76, 0xfffff800
	s_nop 0
	global_load_lds_dwordx4 v164, s[64:65] offset:2048
	s_waitcnt vmcnt(8)
	s_waitcnt lgkmcnt(0)
	s_nop 0
	s_setprio 1
	s_barrier
	v_mfma_f32_16x16x32_bf16 v[92:95], v[56:59], v[180:183], v[92:95]
	v_mfma_f32_16x16x32_bf16 v[88:91], v[64:67], v[180:183], v[88:91]
	v_mfma_f32_16x16x32_bf16 v[44:47], v[56:59], v[200:203], v[44:47]
	v_mfma_f32_16x16x32_bf16 v[40:43], v[64:67], v[200:203], v[40:43]
	v_mfma_f32_16x16x32_bf16 v[28:31], v[56:59], v[208:211], v[28:31]
	v_mfma_f32_16x16x32_bf16 v[24:27], v[64:67], v[208:211], v[24:27]
	v_mfma_f32_16x16x32_bf16 v[12:15], v[56:59], v[216:219], v[12:15]
	v_mfma_f32_16x16x32_bf16 v[8:11], v[64:67], v[216:219], v[8:11]
	v_mfma_f32_16x16x32_bf16 v[92:95], v[60:63], v[196:199], v[92:95]
	v_mfma_f32_16x16x32_bf16 v[88:91], v[68:71], v[196:199], v[88:91]
	v_mfma_f32_16x16x32_bf16 v[44:47], v[60:63], v[204:207], v[44:47]
	v_mfma_f32_16x16x32_bf16 v[40:43], v[68:71], v[204:207], v[40:43]
	v_mfma_f32_16x16x32_bf16 v[28:31], v[60:63], v[212:215], v[28:31]
	v_mfma_f32_16x16x32_bf16 v[24:27], v[68:71], v[212:215], v[24:27]
	v_mfma_f32_16x16x32_bf16 v[12:15], v[60:63], v[220:223], v[12:15]
	v_mfma_f32_16x16x32_bf16 v[8:11], v[68:71], v[220:223], v[8:11]
	v_mfma_f32_16x16x32_bf16 v[48:51], v[72:75], v[180:183], v[48:51]
	v_mfma_f32_16x16x32_bf16 v[52:55], v[80:83], v[180:183], v[52:55]
	v_mfma_f32_16x16x32_bf16 v[32:35], v[72:75], v[200:203], v[32:35]
	v_mfma_f32_16x16x32_bf16 v[36:39], v[80:83], v[200:203], v[36:39]
	v_mfma_f32_16x16x32_bf16 v[16:19], v[72:75], v[208:211], v[16:19]
	v_mfma_f32_16x16x32_bf16 v[20:23], v[80:83], v[208:211], v[20:23]
	v_mfma_f32_16x16x32_bf16 v[0:3], v[72:75], v[216:219], v[0:3]
	v_mfma_f32_16x16x32_bf16 v[4:7], v[80:83], v[216:219], v[4:7]
	v_mfma_f32_16x16x32_bf16 v[48:51], v[76:79], v[196:199], v[48:51]
	v_mfma_f32_16x16x32_bf16 v[68:71], v[84:87], v[196:199], v[52:55]
	v_mfma_f32_16x16x32_bf16 v[32:35], v[76:79], v[204:207], v[32:35]
	s_add_i32 s93, s93, 2
	v_mfma_f32_16x16x32_bf16 v[36:39], v[84:87], v[204:207], v[36:39]
	s_add_u32 s90, s90, 0x1000
	v_mfma_f32_16x16x32_bf16 v[16:19], v[76:79], v[212:215], v[16:19]
	s_addc_u32 s91, s91, 0
	v_mfma_f32_16x16x32_bf16 v[20:23], v[84:87], v[212:215], v[20:23]
	s_cmp_gt_u32 s93, 61
	v_mfma_f32_16x16x32_bf16 v[0:3], v[76:79], v[220:223], v[0:3]
	s_mov_b64 s[14:15], s[60:61]
	v_mfma_f32_16x16x32_bf16 v[4:7], v[84:87], v[220:223], v[4:7]
	s_barrier
	s_setprio 0
	s_cbranch_scc0 .LBB0_639
	s_and_b64 vcc, exec, s[42:43]
	s_cbranch_vccz .LBB0_642
	s_barrier

.LBB0_771:
	s_add_i32 m0, s44, 0xc000
	ds_read_b128 v[128:131], v188
	ds_read_b128 v[132:135], v188 offset:1024
	ds_read_b128 v[136:139], v188 offset:2048
	ds_read_b128 v[140:143], v188 offset:3072
	ds_read_b128 v[144:147], v189
	ds_read_b128 v[148:151], v189 offset:1024
	ds_read_b128 v[166:169], v189 offset:2048
	ds_read_b128 v[170:173], v189 offset:3072
	s_add_u32 s3, s38, 0xffd50800
	s_addc_u32 s16, s39, -1
	s_cmpk_eq_i32 s68, 0xa8
	s_cselect_b32 s43, s7, s16
	s_cselect_b32 s42, s6, s3
	s_cselect_b32 s41, s21, s67
	s_cselect_b32 s40, s20, s66
	ds_read_b128 v[174:177], v190
	ds_read_b128 v[178:181], v190 offset:1024
	ds_read_b128 v[182:185], v190 offset:2048
	ds_read_b128 v[196:199], v190 offset:3072
	ds_read_b128 v[200:203], v190 offset:4096
	ds_read_b128 v[204:207], v190 offset:5120
	ds_read_b128 v[208:211], v190 offset:6144
	ds_read_b128 v[212:215], v190 offset:7168
	global_load_lds_dwordx4 v158, s[38:39]
	s_add_i32 m0, s44, 0xe000
	s_nop 0
	global_load_lds_dwordx4 v160, s[38:39]
	s_waitcnt vmcnt(8)
	s_waitcnt lgkmcnt(0)
	s_setprio 1
	s_barrier
	v_mfma_f32_16x16x32_bf16 v[124:127], v[128:131], v[174:177], v[124:127]
	v_mfma_f32_16x16x32_bf16 v[120:123], v[136:139], v[174:177], v[120:123]
	v_mfma_f32_16x16x32_bf16 v[108:111], v[128:131], v[182:185], v[108:111]
	v_mfma_f32_16x16x32_bf16 v[104:107], v[136:139], v[182:185], v[104:107]
	v_mfma_f32_16x16x32_bf16 v[92:95], v[128:131], v[200:203], v[92:95]
	v_mfma_f32_16x16x32_bf16 v[88:91], v[136:139], v[200:203], v[88:91]
	v_mfma_f32_16x16x32_bf16 v[76:79], v[128:131], v[208:211], v[76:79]
	v_mfma_f32_16x16x32_bf16 v[72:75], v[136:139], v[208:211], v[72:75]
	v_mfma_f32_16x16x32_bf16 v[124:127], v[132:135], v[178:181], v[124:127]
	v_mfma_f32_16x16x32_bf16 v[120:123], v[140:143], v[178:181], v[120:123]
	v_mfma_f32_16x16x32_bf16 v[108:111], v[132:135], v[196:199], v[108:111]
	v_mfma_f32_16x16x32_bf16 v[104:107], v[140:143], v[196:199], v[104:107]
	v_mfma_f32_16x16x32_bf16 v[92:95], v[132:135], v[204:207], v[92:95]
	v_mfma_f32_16x16x32_bf16 v[88:91], v[140:143], v[204:207], v[88:91]
	v_mfma_f32_16x16x32_bf16 v[76:79], v[132:135], v[212:215], v[76:79]
	v_mfma_f32_16x16x32_bf16 v[72:75], v[140:143], v[212:215], v[72:75]
	v_mfma_f32_16x16x32_bf16 v[116:119], v[144:147], v[174:177], v[116:119]
	v_mfma_f32_16x16x32_bf16 v[112:115], v[166:169], v[174:177], v[112:115]
	v_mfma_f32_16x16x32_bf16 v[100:103], v[144:147], v[182:185], v[100:103]
	v_mfma_f32_16x16x32_bf16 v[96:99], v[166:169], v[182:185], v[96:99]
	v_mfma_f32_16x16x32_bf16 v[84:87], v[144:147], v[200:203], v[84:87]
	v_mfma_f32_16x16x32_bf16 v[80:83], v[166:169], v[200:203], v[80:83]
	v_mfma_f32_16x16x32_bf16 v[68:71], v[144:147], v[208:211], v[68:71]
	v_mfma_f32_16x16x32_bf16 v[64:67], v[166:169], v[208:211], v[64:67]
	v_mfma_f32_16x16x32_bf16 v[116:119], v[148:151], v[178:181], v[116:119]
	v_mfma_f32_16x16x32_bf16 v[112:115], v[170:173], v[178:181], v[112:115]
	v_mfma_f32_16x16x32_bf16 v[100:103], v[148:151], v[196:199], v[100:103]
	v_mfma_f32_16x16x32_bf16 v[96:99], v[170:173], v[196:199], v[96:99]
	v_mfma_f32_16x16x32_bf16 v[84:87], v[148:151], v[204:207], v[84:87]
	v_mfma_f32_16x16x32_bf16 v[80:83], v[170:173], v[204:207], v[80:83]
	v_mfma_f32_16x16x32_bf16 v[68:71], v[148:151], v[212:215], v[68:71]
	v_mfma_f32_16x16x32_bf16 v[64:67], v[170:173], v[212:215], v[64:67]
	s_barrier
	s_setprio 0
	s_add_i32 s3, s55, s19
	s_mov_b32 m0, s3
	ds_read_b128 v[174:177], v190 offset:16384
	ds_read_b128 v[178:181], v190 offset:17408
	ds_read_b128 v[182:185], v190 offset:18432
	ds_read_b128 v[196:199], v190 offset:19456
	ds_read_b128 v[200:203], v190 offset:20480
	ds_read_b128 v[204:207], v190 offset:21504
	ds_read_b128 v[208:211], v190 offset:22528
	ds_read_b128 v[212:215], v190 offset:23552
	global_load_lds_dwordx4 v152, s[40:41]
	s_add_i32 m0, s3, 0x2000
	s_add_u32 s16, s40, 0x2b0000
	s_addc_u32 s17, s41, 0
	global_load_lds_dwordx4 v154, s[40:41]
	s_add_i32 s3, s56, s19
	s_mov_b32 m0, s3
	s_nop 0
	global_load_lds_dwordx4 v152, s[16:17]
	s_add_i32 m0, s3, 0x2000
	s_nop 0
	global_load_lds_dwordx4 v154, s[16:17]
	s_mov_b32 m0, s44
	s_nop 0
	global_load_lds_dwordx4 v152, s[42:43]
	s_mov_b32 m0, s45
	s_nop 0
	global_load_lds_dwordx4 v154, s[42:43]
	s_waitcnt vmcnt(8)
	s_waitcnt lgkmcnt(0)
	s_nop 0
	s_setprio 1
	s_barrier
	v_mfma_f32_16x16x32_bf16 v[60:63], v[128:131], v[174:177], v[60:63]
	v_mfma_f32_16x16x32_bf16 v[56:59], v[136:139], v[174:177], v[56:59]
	v_mfma_f32_16x16x32_bf16 v[44:47], v[128:131], v[182:185], v[44:47]
	v_mfma_f32_16x16x32_bf16 v[40:43], v[136:139], v[182:185], v[40:43]
	v_mfma_f32_16x16x32_bf16 v[28:31], v[128:131], v[200:203], v[28:31]
	v_mfma_f32_16x16x32_bf16 v[24:27], v[136:139], v[200:203], v[24:27]
	v_mfma_f32_16x16x32_bf16 v[12:15], v[128:131], v[208:211], v[12:15]
	v_mfma_f32_16x16x32_bf16 v[8:11], v[136:139], v[208:211], v[8:11]
	v_mfma_f32_16x16x32_bf16 v[60:63], v[132:135], v[178:181], v[60:63]
	v_mfma_f32_16x16x32_bf16 v[56:59], v[140:143], v[178:181], v[56:59]
	v_mfma_f32_16x16x32_bf16 v[44:47], v[132:135], v[196:199], v[44:47]
	v_mfma_f32_16x16x32_bf16 v[40:43], v[140:143], v[196:199], v[40:43]
	v_mfma_f32_16x16x32_bf16 v[28:31], v[132:135], v[204:207], v[28:31]
	v_mfma_f32_16x16x32_bf16 v[24:27], v[140:143], v[204:207], v[24:27]
	v_mfma_f32_16x16x32_bf16 v[12:15], v[132:135], v[212:215], v[12:15]
	v_mfma_f32_16x16x32_bf16 v[8:11], v[140:143], v[212:215], v[8:11]
	v_mfma_f32_16x16x32_bf16 v[52:55], v[144:147], v[174:177], v[52:55]
	v_mfma_f32_16x16x32_bf16 v[48:51], v[166:169], v[174:177], v[48:51]
	v_mfma_f32_16x16x32_bf16 v[36:39], v[144:147], v[182:185], v[36:39]
	v_mfma_f32_16x16x32_bf16 v[32:35], v[166:169], v[182:185], v[32:35]
	v_mfma_f32_16x16x32_bf16 v[20:23], v[144:147], v[200:203], v[20:23]
	v_mfma_f32_16x16x32_bf16 v[16:19], v[166:169], v[200:203], v[16:19]
	v_mfma_f32_16x16x32_bf16 v[4:7], v[144:147], v[208:211], v[4:7]
	v_mfma_f32_16x16x32_bf16 v[0:3], v[166:169], v[208:211], v[0:3]
	v_mfma_f32_16x16x32_bf16 v[52:55], v[148:151], v[178:181], v[52:55]
	v_mfma_f32_16x16x32_bf16 v[48:51], v[170:173], v[178:181], v[48:51]
	v_mfma_f32_16x16x32_bf16 v[36:39], v[148:151], v[196:199], v[36:39]
	v_mfma_f32_16x16x32_bf16 v[32:35], v[170:173], v[196:199], v[32:35]
	v_mfma_f32_16x16x32_bf16 v[20:23], v[148:151], v[204:207], v[20:23]
	v_mfma_f32_16x16x32_bf16 v[16:19], v[170:173], v[204:207], v[16:19]
	v_mfma_f32_16x16x32_bf16 v[4:7], v[148:151], v[212:215], v[4:7]
	v_mfma_f32_16x16x32_bf16 v[0:3], v[170:173], v[212:215], v[0:3]
	s_barrier
	s_setprio 0
	s_add_i32 s3, 0, 0x18000
	s_add_i32 s33, 0, 0x1c000
	v_add_u32_e32 v140, s3, v187
	v_add_u32_e32 v170, s33, v187
	s_add_u32 s16, s42, 0x2b0000
	s_addc_u32 s17, s43, 0
	s_mov_b32 m0, s46
	ds_read_b128 v[128:131], v140
	ds_read_b128 v[132:135], v140 offset:1024
	ds_read_b128 v[136:139], v140 offset:2048
	ds_read_b128 v[140:143], v140 offset:3072
	ds_read_b128 v[144:147], v170
	ds_read_b128 v[148:151], v170 offset:1024
	ds_read_b128 v[166:169], v170 offset:2048
	ds_read_b128 v[170:173], v170 offset:3072
	ds_read_b128 v[174:177], v190 offset:32768
	ds_read_b128 v[178:181], v190 offset:33792
	ds_read_b128 v[182:185], v190 offset:34816
	ds_read_b128 v[196:199], v190 offset:35840
	ds_read_b128 v[200:203], v190 offset:36864
	ds_read_b128 v[204:207], v190 offset:37888
	ds_read_b128 v[208:211], v190 offset:38912
	ds_read_b128 v[212:215], v190 offset:39936
	global_load_lds_dwordx4 v152, s[16:17]
	s_mov_b32 m0, s47
	s_nop 0
	global_load_lds_dwordx4 v154, s[16:17]
	s_waitcnt vmcnt(8)
	s_waitcnt lgkmcnt(0)
	s_setprio 1
	s_barrier
	v_mfma_f32_16x16x32_bf16 v[124:127], v[128:131], v[174:177], v[124:127]
	v_mfma_f32_16x16x32_bf16 v[120:123], v[136:139], v[174:177], v[120:123]
	v_mfma_f32_16x16x32_bf16 v[108:111], v[128:131], v[182:185], v[108:111]
	v_mfma_f32_16x16x32_bf16 v[104:107], v[136:139], v[182:185], v[104:107]
	v_mfma_f32_16x16x32_bf16 v[92:95], v[128:131], v[200:203], v[92:95]
	v_mfma_f32_16x16x32_bf16 v[88:91], v[136:139], v[200:203], v[88:91]
	v_mfma_f32_16x16x32_bf16 v[76:79], v[128:131], v[208:211], v[76:79]
	v_mfma_f32_16x16x32_bf16 v[72:75], v[136:139], v[208:211], v[72:75]
	v_mfma_f32_16x16x32_bf16 v[124:127], v[132:135], v[178:181], v[124:127]
	v_mfma_f32_16x16x32_bf16 v[120:123], v[140:143], v[178:181], v[120:123]
	v_mfma_f32_16x16x32_bf16 v[108:111], v[132:135], v[196:199], v[108:111]
	v_mfma_f32_16x16x32_bf16 v[104:107], v[140:143], v[196:199], v[104:107]
	v_mfma_f32_16x16x32_bf16 v[92:95], v[132:135], v[204:207], v[92:95]
	v_mfma_f32_16x16x32_bf16 v[88:91], v[140:143], v[204:207], v[88:91]
	v_mfma_f32_16x16x32_bf16 v[76:79], v[132:135], v[212:215], v[76:79]
	v_mfma_f32_16x16x32_bf16 v[72:75], v[140:143], v[212:215], v[72:75]
	v_mfma_f32_16x16x32_bf16 v[116:119], v[144:147], v[174:177], v[116:119]
	v_mfma_f32_16x16x32_bf16 v[112:115], v[166:169], v[174:177], v[112:115]
	v_mfma_f32_16x16x32_bf16 v[100:103], v[144:147], v[182:185], v[100:103]
	v_mfma_f32_16x16x32_bf16 v[96:99], v[166:169], v[182:185], v[96:99]
	v_mfma_f32_16x16x32_bf16 v[84:87], v[144:147], v[200:203], v[84:87]
	v_mfma_f32_16x16x32_bf16 v[80:83], v[166:169], v[200:203], v[80:83]
	v_mfma_f32_16x16x32_bf16 v[68:71], v[144:147], v[208:211], v[68:71]
	v_mfma_f32_16x16x32_bf16 v[64:67], v[166:169], v[208:211], v[64:67]
	v_mfma_f32_16x16x32_bf16 v[116:119], v[148:151], v[178:181], v[116:119]
	v_mfma_f32_16x16x32_bf16 v[112:115], v[170:173], v[178:181], v[112:115]
	v_mfma_f32_16x16x32_bf16 v[100:103], v[148:151], v[196:199], v[100:103]
	v_mfma_f32_16x16x32_bf16 v[96:99], v[170:173], v[196:199], v[96:99]
	v_mfma_f32_16x16x32_bf16 v[84:87], v[148:151], v[204:207], v[84:87]
	v_mfma_f32_16x16x32_bf16 v[80:83], v[170:173], v[204:207], v[80:83]
	v_mfma_f32_16x16x32_bf16 v[68:71], v[148:151], v[212:215], v[68:71]
	v_mfma_f32_16x16x32_bf16 v[64:67], v[170:173], v[212:215], v[64:67]
	s_barrier
	s_setprio 0
	s_add_i32 m0, s19, 0x17800
	ds_read_b128 v[174:177], v190 offset:49152
	ds_read_b128 v[178:181], v190 offset:50176
	ds_read_b128 v[182:185], v190 offset:51200
	ds_read_b128 v[196:199], v190 offset:52224
	ds_read_b128 v[200:203], v190 offset:53248
	ds_read_b128 v[204:207], v190 offset:54272
	ds_read_b128 v[208:211], v190 offset:55296
	ds_read_b128 v[212:215], v190 offset:56320
	global_load_lds_dwordx4 v152, s[40:41] offset:2048
	s_add_i32 m0, s19, 0x19800
	s_add_u32 s16, s40, 0x2b0800
	s_addc_u32 s17, s41, 0
	global_load_lds_dwordx4 v154, s[40:41] offset:2048
	s_add_i32 m0, s19, 0x1c000
	s_nop 0
	global_load_lds_dwordx4 v152, s[16:17]
	s_add_i32 m0, s19, 0x1e000
	s_nop 0
	global_load_lds_dwordx4 v154, s[16:17]
	s_add_i32 m0, s50, 0xfffff800
	s_nop 0
	global_load_lds_dwordx4 v152, s[42:43] offset:2048
	s_add_i32 m0, s51, 0xfffff800
	s_nop 0
	global_load_lds_dwordx4 v154, s[42:43] offset:2048
	s_waitcnt vmcnt(8)
	s_waitcnt lgkmcnt(0)
	s_nop 0
	s_setprio 1
	s_barrier
	v_mfma_f32_16x16x32_bf16 v[60:63], v[128:131], v[174:177], v[60:63]
	v_mfma_f32_16x16x32_bf16 v[56:59], v[136:139], v[174:177], v[56:59]
	v_mfma_f32_16x16x32_bf16 v[44:47], v[128:131], v[182:185], v[44:47]
	v_mfma_f32_16x16x32_bf16 v[40:43], v[136:139], v[182:185], v[40:43]
	v_mfma_f32_16x16x32_bf16 v[28:31], v[128:131], v[200:203], v[28:31]
	v_mfma_f32_16x16x32_bf16 v[24:27], v[136:139], v[200:203], v[24:27]
	v_mfma_f32_16x16x32_bf16 v[12:15], v[128:131], v[208:211], v[12:15]
	v_mfma_f32_16x16x32_bf16 v[8:11], v[136:139], v[208:211], v[8:11]
	v_mfma_f32_16x16x32_bf16 v[60:63], v[132:135], v[178:181], v[60:63]
	v_mfma_f32_16x16x32_bf16 v[56:59], v[140:143], v[178:181], v[56:59]
	v_mfma_f32_16x16x32_bf16 v[44:47], v[132:135], v[196:199], v[44:47]
	v_mfma_f32_16x16x32_bf16 v[40:43], v[140:143], v[196:199], v[40:43]
	v_mfma_f32_16x16x32_bf16 v[28:31], v[132:135], v[204:207], v[28:31]
	v_mfma_f32_16x16x32_bf16 v[24:27], v[140:143], v[204:207], v[24:27]
	v_mfma_f32_16x16x32_bf16 v[12:15], v[132:135], v[212:215], v[12:15]
	v_mfma_f32_16x16x32_bf16 v[8:11], v[140:143], v[212:215], v[8:11]
	v_mfma_f32_16x16x32_bf16 v[52:55], v[144:147], v[174:177], v[52:55]
	v_mfma_f32_16x16x32_bf16 v[48:51], v[166:169], v[174:177], v[48:51]
	v_mfma_f32_16x16x32_bf16 v[36:39], v[144:147], v[182:185], v[36:39]
	v_mfma_f32_16x16x32_bf16 v[32:35], v[166:169], v[182:185], v[32:35]
	v_mfma_f32_16x16x32_bf16 v[20:23], v[144:147], v[200:203], v[20:23]
	v_mfma_f32_16x16x32_bf16 v[16:19], v[166:169], v[200:203], v[16:19]
	v_mfma_f32_16x16x32_bf16 v[4:7], v[144:147], v[208:211], v[4:7]
	v_mfma_f32_16x16x32_bf16 v[0:3], v[166:169], v[208:211], v[0:3]
	v_mfma_f32_16x16x32_bf16 v[52:55], v[148:151], v[178:181], v[52:55]
	v_mfma_f32_16x16x32_bf16 v[48:51], v[170:173], v[178:181], v[48:51]
	v_mfma_f32_16x16x32_bf16 v[36:39], v[148:151], v[196:199], v[36:39]
	s_add_i32 s68, s68, 2
	v_mfma_f32_16x16x32_bf16 v[32:35], v[170:173], v[196:199], v[32:35]
	s_add_u32 s38, s38, 0x1000
	v_mfma_f32_16x16x32_bf16 v[20:23], v[148:151], v[204:207], v[20:23]
	s_addc_u32 s39, s39, 0
	v_mfma_f32_16x16x32_bf16 v[16:19], v[170:173], v[204:207], v[16:19]
	s_add_u32 s66, s66, 0x1000
	v_mfma_f32_16x16x32_bf16 v[4:7], v[148:151], v[212:215], v[4:7]
	s_addc_u32 s67, s67, 0
	v_mfma_f32_16x16x32_bf16 v[0:3], v[170:173], v[212:215], v[0:3]
	s_cmpk_gt_u32 s68, 0xa9
	s_barrier
	s_setprio 0
	s_cbranch_scc0 .LBB0_771
	s_and_b64 vcc, exec, s[14:15]
	s_cbranch_vccz .LBB0_774
	s_barrier
